# SwiGLU epilogue: c1/c2/row-statistics loads issued before the wave-half alignment barrier
# speedup vs baseline: 1.0036x; 1.0036x over previous
; #define PG8_STAGE(bufoff, gbase, voff) do { _Pragma("unroll") for (int _i = 0; _i < 2; ++_i) \
;         __builtin_amdgcn_global_load_lds((const unsigned*)((const char*)(gbase) + (voff)[_i]), (PG8_LAS unsigned*)(lds + (bufoff) + ldsw + _i * 8192), 16, 0, 0); } while (0)
; #define PG8_LDA(dst, b, h) do { _Pragma("unroll") for (int m = 0; m < 4; ++m) _Pragma("unroll") for (int k = 0; k < 2; ++k) dst[m][k] = *(const PG8_LAS bf16x8*)(lds + PG8_SA(b, h) + aoff + m * 2048 + k * 1024); } while (0)
; #define PG8_LDB(dst, b, h) do { _Pragma("unroll") for (int n = 0; n < 2; ++n) _Pragma("unroll") for (int k = 0; k < 2; ++k) dst[n][k] = *(const PG8_LAS bf16x8*)(lds + PG8_SB(b, h) + boff + n * 2048 + k * 1024); } while (0)
; #define PG8_MMA(ai, bj, At, Bt) do { __builtin_amdgcn_s_setprio(1); _Pragma("unroll") for (int m = 0; m < 4; ++m) _Pragma("unroll") for (int n = 0; n < 2; ++n) _Pragma("unroll") for (int k = 0; k < 2; ++k) \
;         acc[ai][bj][m][n] = __builtin_amdgcn_mfma_f32_16x16x32_bf16(Bt[n][k], At[m][k], acc[ai][bj][m][n], 0, 0, 0); __builtin_amdgcn_s_setprio(0); } while (0)
; template <class Epi, class Sched, bool ALIGN_EPI = false, bool SP2 = false>
; __device__ __forceinline__ void gemm_phase(PG8_LAS unsigned char* lds, const Gemm g, const Sched& S, const Epi& E, int wv) {
;     ...
;         const bool has_next = S.next(ui + 1, nxt);
;         const char* nA = has_next ? (const char*)g.A + (size_t)nxt.pm * tstepA : cA; const char* nB = has_next ? (const char*)g.Bt + (size_t)nxt.pn * tstepB : cB;
; #pragma unroll 1
;         for (int t = 0; t < nt; t += 2) {
;             const bool last = (t == nt - 2);
;             const char* a1 = cA + (size_t)(t + 1) * kstep;
;             const char* a2 = last ? nA : cA + (size_t)(t + 2) * kstep; const char* b2 = last ? nB : cB + (size_t)(t + 2) * kstep;
;             const char* a3 = a2 + kstep; const char* b3 = b2 + kstep;
;             if (last && has_next) S.a_ready(nxt);
;             if constexpr (SP2) {
;             PG8_LDB(B0, 0, 0); PG8_LDB(B1, 0, 1); PG8_SCHED; PG8_LDA(At, 0, 0); PG8_STAGE(PG8_SA(1, 1), a1 + hstepA, voffA);
;             PG8_WAIT_V(8); PG8_WAIT_L(0); PG8_BAR; PG8_MMA(0, 0, At, B0); PG8_MMA(0, 1, At, B1); PG8_BAR; PG8_SCHED;
;             PG8_LDA(At, 0, 1); PG8_STAGE(PG8_SB(0, 0), b2, voffB); PG8_STAGE(PG8_SB(0, 1), b2 + hstepB, voffB); PG8_STAGE(PG8_SA(0, 0), a2, voffA);
.LBB0_1893:
	s_add_u32 s2, s40, 0xfffc0080
	s_addc_u32 s3, s41, -1
	s_add_i32 s60, 0, 0x10000
	s_cmp_eq_u32 s96, 12
	s_cselect_b32 s43, s39, s3
	s_cselect_b32 s42, s92, s2
	s_cselect_b32 s3, s37, s95
	s_cselect_b32 s2, s93, s94
	s_add_i32 s61, 0, 0x14000
	v_add_u32_e32 v46, s60, v180
	v_add_u32_e32 v62, s61, v180
	ds_read_b128 v[34:37], v46
	ds_read_b128 v[38:41], v46 offset:1024
	ds_read_b128 v[42:45], v46 offset:2048
	ds_read_b128 v[46:49], v46 offset:3072
	ds_read_b128 v[50:53], v62
	ds_read_b128 v[54:57], v62 offset:1024
	ds_read_b128 v[58:61], v62 offset:2048
	ds_read_b128 v[62:65], v62 offset:3072
	v_lshl_add_u64 v[176:177], s[40:41], 0, v[168:169]
	s_add_i32 m0, s35, 0xc000
	ds_read_b128 v[172:175], v181
	ds_read_b128 v[182:185], v181 offset:1024
	ds_read_b128 v[220:223], v181 offset:2048
	ds_read_b128 v[224:227], v181 offset:3072
	ds_read_b128 v[228:231], v181 offset:4096
	ds_read_b128 v[242:245], v181 offset:5120
	ds_read_b128 v[246:249], v181 offset:6144
	ds_read_b128 v[250:253], v181 offset:7168
	global_load_lds_dwordx4 v[176:177], off
	v_lshl_add_u64 v[176:177], s[40:41], 0, v[170:171]
	s_add_i32 m0, s35, 0xe000
	s_nop 0
	global_load_lds_dwordx4 v[176:177], off
	s_waitcnt vmcnt(8)
	s_waitcnt lgkmcnt(0)
	s_barrier
	s_setprio 1
	s_waitcnt lgkmcnt(0)
	v_mfma_f32_16x16x32_bf16 v[158:161], v[34:37], v[172:175], v[158:161]
	v_mfma_f32_16x16x32_bf16 v[154:157], v[42:45], v[172:175], v[154:157]
	v_mfma_f32_16x16x32_bf16 v[142:145], v[34:37], v[220:223], v[142:145]
	v_mfma_f32_16x16x32_bf16 v[138:141], v[42:45], v[220:223], v[138:141]
	v_mfma_f32_16x16x32_bf16 v[126:129], v[34:37], v[228:231], v[126:129]
	v_mfma_f32_16x16x32_bf16 v[122:125], v[42:45], v[228:231], v[122:125]
	v_mfma_f32_16x16x32_bf16 v[110:113], v[34:37], v[246:249], v[110:113]
	v_mfma_f32_16x16x32_bf16 v[106:109], v[42:45], v[246:249], v[106:109]
	v_mfma_f32_16x16x32_bf16 v[158:161], v[38:41], v[182:185], v[158:161]
	v_mfma_f32_16x16x32_bf16 v[154:157], v[46:49], v[182:185], v[154:157]
	v_mfma_f32_16x16x32_bf16 v[142:145], v[38:41], v[224:227], v[142:145]
	v_mfma_f32_16x16x32_bf16 v[138:141], v[46:49], v[224:227], v[138:141]
	v_mfma_f32_16x16x32_bf16 v[126:129], v[38:41], v[242:245], v[126:129]
	v_mfma_f32_16x16x32_bf16 v[122:125], v[46:49], v[242:245], v[122:125]
	v_mfma_f32_16x16x32_bf16 v[110:113], v[38:41], v[250:253], v[110:113]
	v_mfma_f32_16x16x32_bf16 v[106:109], v[46:49], v[250:253], v[106:109]
	s_setprio 0
	s_setprio 1
	v_mfma_f32_16x16x32_bf16 v[150:153], v[50:53], v[172:175], v[150:153]
	v_mfma_f32_16x16x32_bf16 v[146:149], v[58:61], v[172:175], v[146:149]
	v_mfma_f32_16x16x32_bf16 v[134:137], v[50:53], v[220:223], v[134:137]
	v_mfma_f32_16x16x32_bf16 v[130:133], v[58:61], v[220:223], v[130:133]
	v_mfma_f32_16x16x32_bf16 v[118:121], v[50:53], v[228:231], v[118:121]
	v_mfma_f32_16x16x32_bf16 v[114:117], v[58:61], v[228:231], v[114:117]
	v_mfma_f32_16x16x32_bf16 v[102:105], v[50:53], v[246:249], v[102:105]
	v_mfma_f32_16x16x32_bf16 v[98:101], v[58:61], v[246:249], v[98:101]
	v_mfma_f32_16x16x32_bf16 v[150:153], v[54:57], v[182:185], v[150:153]
	v_mfma_f32_16x16x32_bf16 v[146:149], v[62:65], v[182:185], v[146:149]
	v_mfma_f32_16x16x32_bf16 v[134:137], v[54:57], v[224:227], v[134:137]
	v_mfma_f32_16x16x32_bf16 v[130:133], v[62:65], v[224:227], v[130:133]
	v_mfma_f32_16x16x32_bf16 v[118:121], v[54:57], v[242:245], v[118:121]
	v_mfma_f32_16x16x32_bf16 v[114:117], v[62:65], v[242:245], v[114:117]
	v_mfma_f32_16x16x32_bf16 v[102:105], v[54:57], v[250:253], v[102:105]
	v_mfma_f32_16x16x32_bf16 v[98:101], v[62:65], v[250:253], v[98:101]
	s_setprio 0
	s_barrier
	s_add_i32 s60, s60, s50
	v_lshl_add_u64 v[176:177], s[2:3], 0, v[0:1]
	s_mov_b32 m0, s60
	ds_read_b128 v[172:175], v181 offset:16384
	ds_read_b128 v[182:185], v181 offset:17408
	ds_read_b128 v[220:223], v181 offset:18432
	ds_read_b128 v[224:227], v181 offset:19456
	ds_read_b128 v[228:231], v181 offset:20480
	ds_read_b128 v[242:245], v181 offset:21504
	ds_read_b128 v[246:249], v181 offset:22528
	ds_read_b128 v[250:253], v181 offset:23552
	global_load_lds_dwordx4 v[176:177], off
	s_add_i32 m0, s60, 0x2000
	s_add_u32 vcc_lo, s2, 0x40000
	v_lshl_add_u64 v[186:187], s[2:3], 0, v[162:163]
	s_addc_u32 vcc_hi, s3, 0
	s_add_i32 s60, s61, s50
	global_load_lds_dwordx4 v[186:187], off
	v_lshl_add_u64 v[196:197], vcc, 0, v[0:1]
	s_mov_b32 m0, s60
	v_lshl_add_u64 v[240:241], s[42:43], 0, v[164:165]
	global_load_lds_dwordx4 v[196:197], off
	v_lshl_add_u64 v[196:197], vcc, 0, v[162:163]
	s_add_i32 m0, s60, 0x2000
	s_nop 0
	global_load_lds_dwordx4 v[196:197], off
	v_lshl_add_u64 v[196:197], s[42:43], 0, v[166:167]
	s_mov_b32 m0, s35
	s_nop 0
	global_load_lds_dwordx4 v[196:197], off
	s_mov_b32 m0, s52
	s_nop 0
	global_load_lds_dwordx4 v[240:241], off
	s_waitcnt vmcnt(8)
	s_waitcnt lgkmcnt(0)
	s_barrier
; #define PG8_STAGE(bufoff, gbase, voff) do { _Pragma("unroll") for (int _i = 0; _i < 2; ++_i) \
;         __builtin_amdgcn_global_load_lds((const unsigned*)((const char*)(gbase) + (voff)[_i]), (PG8_LAS unsigned*)(lds + (bufoff) + ldsw + _i * 8192), 16, 0, 0); } while (0)
; #define PG8_LDA(dst, b, h) do { _Pragma("unroll") for (int m = 0; m < 4; ++m) _Pragma("unroll") for (int k = 0; k < 2; ++k) dst[m][k] = *(const PG8_LAS bf16x8*)(lds + PG8_SA(b, h) + aoff + m * 2048 + k * 1024); } while (0)
; #define PG8_LDB(dst, b, h) do { _Pragma("unroll") for (int n = 0; n < 2; ++n) _Pragma("unroll") for (int k = 0; k < 2; ++k) dst[n][k] = *(const PG8_LAS bf16x8*)(lds + PG8_SB(b, h) + boff + n * 2048 + k * 1024); } while (0)
; #define PG8_MMA(ai, bj, At, Bt) do { __builtin_amdgcn_s_setprio(1); _Pragma("unroll") for (int m = 0; m < 4; ++m) _Pragma("unroll") for (int n = 0; n < 2; ++n) _Pragma("unroll") for (int k = 0; k < 2; ++k) \
;         acc[ai][bj][m][n] = __builtin_amdgcn_mfma_f32_16x16x32_bf16(Bt[n][k], At[m][k], acc[ai][bj][m][n], 0, 0, 0); __builtin_amdgcn_s_setprio(0); } while (0)
; #define PG8_WAIT_V(n) asm volatile("s_waitcnt vmcnt(" #n ")" ::: "memory")
; #define PG8_WAIT_L(n) asm volatile("s_waitcnt lgkmcnt(" #n ")" ::: "memory")
; #define PG8_BAR __builtin_amdgcn_s_barrier()
; #define PG8_SCHED __builtin_amdgcn_sched_barrier(0)
; template <class Epi, class Sched, bool ALIGN_EPI = false, bool SP2 = false>
; __device__ __forceinline__ void gemm_phase(PG8_LAS unsigned char* lds, const Gemm g, const Sched& S, const Epi& E, int wv) {
;     ...
;             PG8_WAIT_V(8); PG8_WAIT_L(0); PG8_BAR; PG8_MMA(1, 0, At, B0); PG8_MMA(1, 1, At, B1); PG8_BAR; PG8_SCHED;
;             PG8_LDB(B0, 1, 0); PG8_LDB(B1, 1, 1); PG8_SCHED; PG8_LDA(At, 1, 0); PG8_STAGE(PG8_SA(0, 1), a2 + hstepA, voffA);
;             PG8_WAIT_V(8); PG8_WAIT_L(0); PG8_BAR; PG8_MMA(0, 0, At, B0); PG8_MMA(0, 1, At, B1); PG8_BAR; PG8_SCHED;
	s_setprio 1
	s_waitcnt lgkmcnt(0)
	v_mfma_f32_16x16x32_bf16 v[94:97], v[34:37], v[172:175], v[94:97]
	v_mfma_f32_16x16x32_bf16 v[90:93], v[42:45], v[172:175], v[90:93]
	v_mfma_f32_16x16x32_bf16 v[78:81], v[34:37], v[220:223], v[78:81]
	v_mfma_f32_16x16x32_bf16 v[74:77], v[42:45], v[220:223], v[74:77]
	v_mfma_f32_16x16x32_bf16 v[30:33], v[34:37], v[228:231], v[30:33]
	v_mfma_f32_16x16x32_bf16 v[26:29], v[42:45], v[228:231], v[26:29]
	v_mfma_f32_16x16x32_bf16 v[14:17], v[34:37], v[246:249], v[14:17]
	v_mfma_f32_16x16x32_bf16 v[10:13], v[42:45], v[246:249], v[10:13]
	v_mfma_f32_16x16x32_bf16 v[94:97], v[38:41], v[182:185], v[94:97]
	v_mfma_f32_16x16x32_bf16 v[90:93], v[46:49], v[182:185], v[90:93]
	v_mfma_f32_16x16x32_bf16 v[78:81], v[38:41], v[224:227], v[78:81]
	v_mfma_f32_16x16x32_bf16 v[74:77], v[46:49], v[224:227], v[74:77]
	v_mfma_f32_16x16x32_bf16 v[30:33], v[38:41], v[242:245], v[30:33]
	v_mfma_f32_16x16x32_bf16 v[26:29], v[46:49], v[242:245], v[26:29]
	v_mfma_f32_16x16x32_bf16 v[14:17], v[38:41], v[250:253], v[14:17]
	v_mfma_f32_16x16x32_bf16 v[10:13], v[46:49], v[250:253], v[10:13]
	s_setprio 0
	s_setprio 1
	v_mfma_f32_16x16x32_bf16 v[22:25], v[50:53], v[228:231], v[22:25]
	v_mfma_f32_16x16x32_bf16 v[18:21], v[58:61], v[228:231], v[18:21]
	v_mfma_f32_16x16x32_bf16 v[6:9], v[50:53], v[246:249], v[6:9]
	v_mfma_f32_16x16x32_bf16 v[2:5], v[58:61], v[246:249], v[2:5]
	v_mfma_f32_16x16x32_bf16 v[34:37], v[50:53], v[172:175], v[86:89]
	v_mfma_f32_16x16x32_bf16 v[38:41], v[58:61], v[172:175], v[82:85]
	v_mfma_f32_16x16x32_bf16 v[42:45], v[50:53], v[220:223], v[70:73]
	v_mfma_f32_16x16x32_bf16 v[46:49], v[58:61], v[220:223], v[66:69]
	v_mfma_f32_16x16x32_bf16 v[22:25], v[54:57], v[242:245], v[22:25]
	v_mfma_f32_16x16x32_bf16 v[18:21], v[62:65], v[242:245], v[18:21]
	v_mfma_f32_16x16x32_bf16 v[6:9], v[54:57], v[250:253], v[6:9]
	v_mfma_f32_16x16x32_bf16 v[2:5], v[62:65], v[250:253], v[2:5]
	v_mfma_f32_16x16x32_bf16 v[34:37], v[54:57], v[182:185], v[34:37]
	v_mfma_f32_16x16x32_bf16 v[38:41], v[62:65], v[182:185], v[38:41]
	v_mfma_f32_16x16x32_bf16 v[42:45], v[54:57], v[224:227], v[42:45]
	v_mfma_f32_16x16x32_bf16 v[46:49], v[62:65], v[224:227], v[46:49]
	s_setprio 0
	s_barrier
	s_add_i32 s60, 0, 0x18000
	s_add_i32 s61, 0, 0x1c000
	v_add_u32_e32 v62, s60, v180
	v_add_u32_e32 v66, s61, v180
	ds_read_b128 v[50:53], v62
	ds_read_b128 v[54:57], v62 offset:1024
	ds_read_b128 v[58:61], v62 offset:2048
	ds_read_b128 v[62:65], v62 offset:3072
	ds_read_b128 v[172:175], v66
	ds_read_b128 v[182:185], v66 offset:1024
	ds_read_b128 v[220:223], v66 offset:2048
	ds_read_b128 v[224:227], v66 offset:3072
	s_add_u32 s42, s42, 0x40000
	s_addc_u32 s43, s43, 0
	s_mov_b32 m0, s53
	v_lshl_add_u64 v[232:233], s[42:43], 0, v[166:167]
	ds_read_b128 v[66:69], v181 offset:32768
	ds_read_b128 v[70:73], v181 offset:33792
	ds_read_b128 v[82:85], v181 offset:34816
	ds_read_b128 v[86:89], v181 offset:35840
	ds_read_b128 v[228:231], v181 offset:36864
	ds_read_b128 v[242:245], v181 offset:37888
	ds_read_b128 v[246:249], v181 offset:38912
	ds_read_b128 v[250:253], v181 offset:39936
	global_load_lds_dwordx4 v[232:233], off
	v_lshl_add_u64 v[232:233], s[42:43], 0, v[164:165]
	s_mov_b32 m0, s55
	s_nop 0
	global_load_lds_dwordx4 v[232:233], off
	s_waitcnt vmcnt(8)
	s_waitcnt lgkmcnt(0)
	s_barrier
	s_setprio 1
	s_waitcnt lgkmcnt(0)
	v_mfma_f32_16x16x32_bf16 v[158:161], v[50:53], v[66:69], v[158:161]
	v_mfma_f32_16x16x32_bf16 v[154:157], v[58:61], v[66:69], v[154:157]
	v_mfma_f32_16x16x32_bf16 v[142:145], v[50:53], v[82:85], v[142:145]
	v_mfma_f32_16x16x32_bf16 v[138:141], v[58:61], v[82:85], v[138:141]
	v_mfma_f32_16x16x32_bf16 v[126:129], v[50:53], v[228:231], v[126:129]
	v_mfma_f32_16x16x32_bf16 v[122:125], v[58:61], v[228:231], v[122:125]
	v_mfma_f32_16x16x32_bf16 v[110:113], v[50:53], v[246:249], v[110:113]
	v_mfma_f32_16x16x32_bf16 v[106:109], v[58:61], v[246:249], v[106:109]
	v_mfma_f32_16x16x32_bf16 v[158:161], v[54:57], v[70:73], v[158:161]
	v_mfma_f32_16x16x32_bf16 v[154:157], v[62:65], v[70:73], v[154:157]
	v_mfma_f32_16x16x32_bf16 v[142:145], v[54:57], v[86:89], v[142:145]
	v_mfma_f32_16x16x32_bf16 v[138:141], v[62:65], v[86:89], v[138:141]
	v_mfma_f32_16x16x32_bf16 v[126:129], v[54:57], v[242:245], v[126:129]
	v_mfma_f32_16x16x32_bf16 v[122:125], v[62:65], v[242:245], v[122:125]
	v_mfma_f32_16x16x32_bf16 v[110:113], v[54:57], v[250:253], v[110:113]
	v_mfma_f32_16x16x32_bf16 v[106:109], v[62:65], v[250:253], v[106:109]
	s_setprio 0
	s_setprio 1
	v_mfma_f32_16x16x32_bf16 v[150:153], v[172:175], v[66:69], v[150:153]
	v_mfma_f32_16x16x32_bf16 v[66:69], v[220:223], v[66:69], v[146:149]
	v_mfma_f32_16x16x32_bf16 v[146:149], v[224:227], v[70:73], v[66:69]
	v_mfma_f32_16x16x32_bf16 v[66:69], v[172:175], v[82:85], v[134:137]
	v_mfma_f32_16x16x32_bf16 v[134:137], v[182:185], v[86:89], v[66:69]
	v_mfma_f32_16x16x32_bf16 v[66:69], v[220:223], v[82:85], v[130:133]
	v_mfma_f32_16x16x32_bf16 v[130:133], v[224:227], v[86:89], v[66:69]
	v_mfma_f32_16x16x32_bf16 v[66:69], v[172:175], v[228:231], v[118:121]
	v_mfma_f32_16x16x32_bf16 v[118:121], v[182:185], v[242:245], v[66:69]
	v_mfma_f32_16x16x32_bf16 v[66:69], v[220:223], v[228:231], v[114:117]
	v_mfma_f32_16x16x32_bf16 v[114:117], v[224:227], v[242:245], v[66:69]
	v_mfma_f32_16x16x32_bf16 v[66:69], v[172:175], v[246:249], v[102:105]
	v_mfma_f32_16x16x32_bf16 v[102:105], v[182:185], v[250:253], v[66:69]
	v_mfma_f32_16x16x32_bf16 v[66:69], v[220:223], v[246:249], v[98:101]
	v_mfma_f32_16x16x32_bf16 v[150:153], v[182:185], v[70:73], v[150:153]
	v_mfma_f32_16x16x32_bf16 v[98:101], v[224:227], v[250:253], v[66:69]
	s_setprio 0
	s_barrier
; #define PG8_STAGE(bufoff, gbase, voff) do { _Pragma("unroll") for (int _i = 0; _i < 2; ++_i) \
;         __builtin_amdgcn_global_load_lds((const unsigned*)((const char*)(gbase) + (voff)[_i]), (PG8_LAS unsigned*)(lds + (bufoff) + ldsw + _i * 8192), 16, 0, 0); } while (0)
; #define PG8_LDA(dst, b, h) do { _Pragma("unroll") for (int m = 0; m < 4; ++m) _Pragma("unroll") for (int k = 0; k < 2; ++k) dst[m][k] = *(const PG8_LAS bf16x8*)(lds + PG8_SA(b, h) + aoff + m * 2048 + k * 1024); } while (0)
; #define PG8_MMA(ai, bj, At, Bt) do { __builtin_amdgcn_s_setprio(1); _Pragma("unroll") for (int m = 0; m < 4; ++m) _Pragma("unroll") for (int n = 0; n < 2; ++n) _Pragma("unroll") for (int k = 0; k < 2; ++k) \
;         acc[ai][bj][m][n] = __builtin_amdgcn_mfma_f32_16x16x32_bf16(Bt[n][k], At[m][k], acc[ai][bj][m][n], 0, 0, 0); __builtin_amdgcn_s_setprio(0); } while (0)
; #define PG8_WAIT_V(n) asm volatile("s_waitcnt vmcnt(" #n ")" ::: "memory")
; #define PG8_WAIT_L(n) asm volatile("s_waitcnt lgkmcnt(" #n ")" ::: "memory")
; #define PG8_BAR __builtin_amdgcn_s_barrier()
; template <class Epi, class Sched, bool ALIGN_EPI = false, bool SP2 = false>
; __device__ __forceinline__ void gemm_phase(PG8_LAS unsigned char* lds, const Gemm g, const Sched& S, const Epi& E, int wv) {
;     ...
;             PG8_LDA(At, 1, 1); PG8_STAGE(PG8_SB(1, 0), b3, voffB); PG8_STAGE(PG8_SB(1, 1), b3 + hstepB, voffB); PG8_STAGE(PG8_SA(1, 0), a3, voffA);
;             PG8_WAIT_V(8); PG8_WAIT_L(0); PG8_BAR; PG8_MMA(1, 0, At, B0); PG8_MMA(1, 1, At, B1); PG8_BAR; PG8_SCHED;
;     ...
;         if constexpr (ALIGN_EPI) { if (wr == 0) PG8_BAR; }
; DI void row_stats(const float* STAT, int row, int fq, int lane, float& mu, float& rstd) {
;     const f32x4 a = *(const f32x4*)(STAT + (size_t)row * 32 + fq * 8), b = *(const f32x4*)(STAT + (size_t)row * 32 + fq * 8 + 4);
;     DI void operator()(const f32x4 (&acc)[2][2][4][2], const pg8::Unit& u, int wr, int wc, int fr, int fq) const {
;     ...
;         const int row0 = u.pm * 256 + wr * 64 + fr, col0 = u.pn * 128 + wc * 32 + 8 * fq, lane = fq * 16 + fr, cc = u.pn * 256 + wc * 32 + 8 * fq;
;         f32x4 c1[2][2], c2[2][2];
; #pragma unroll
;         for (int bj = 0; bj < 2; ++bj)
; #pragma unroll
;             for (int n = 0; n < 2; ++n) { c1[bj][n] = *(const f32x4*)(C1 + cc + bj * 128 + n * 4); c2[bj][n] = *(const f32x4*)(C2 + cc + bj * 128 + n * 4); }
	s_add_i32 s42, s60, s50
	v_lshl_add_u64 v[82:83], v[176:177], 0, s[62:63]
	s_mov_b32 m0, s42
	s_nop 0
	ds_read_b128 v[66:69], v181 offset:49152
	ds_read_b128 v[70:73], v181 offset:50176
	ds_read_b128 v[228:231], v181 offset:51200
	ds_read_b128 v[242:245], v181 offset:52224
	ds_read_b128 v[246:249], v181 offset:53248
	ds_read_b128 v[250:253], v181 offset:54272
	ds_read_b128 v[232:235], v181 offset:55296
	ds_read_b128 v[236:239], v181 offset:56320
	global_load_lds_dwordx4 v[82:83], off
	s_add_i32 m0, s42, 0x2000
	s_add_u32 s2, s2, 0x40080
	v_lshl_add_u64 v[82:83], v[186:187], 0, s[62:63]
	s_addc_u32 s3, s3, 0
	s_add_i32 s42, s61, s50
	global_load_lds_dwordx4 v[82:83], off
	v_lshl_add_u64 v[82:83], s[2:3], 0, v[0:1]
	s_mov_b32 m0, s42
	s_nop 0
	global_load_lds_dwordx4 v[82:83], off
	v_lshl_add_u64 v[82:83], s[2:3], 0, v[162:163]
	s_add_i32 m0, s42, 0x2000
	s_nop 0
	global_load_lds_dwordx4 v[82:83], off
	v_lshl_add_u64 v[82:83], v[196:197], 0, s[62:63]
	s_mov_b32 m0, s83
	s_nop 0
	global_load_lds_dwordx4 v[82:83], off
	v_lshl_add_u64 v[82:83], v[240:241], 0, s[62:63]
	s_mov_b32 m0, s87
	s_nop 0
	global_load_lds_dwordx4 v[82:83], off
	s_waitcnt vmcnt(8)
	s_waitcnt lgkmcnt(0)
	s_barrier
	s_setprio 1
	s_waitcnt lgkmcnt(0)
	v_mfma_f32_16x16x32_bf16 v[82:85], v[50:53], v[66:69], v[94:97]
	v_mfma_f32_16x16x32_bf16 v[94:97], v[54:57], v[70:73], v[82:85]
	v_mfma_f32_16x16x32_bf16 v[82:85], v[58:61], v[66:69], v[90:93]
	v_mfma_f32_16x16x32_bf16 v[78:81], v[50:53], v[228:231], v[78:81]
	v_mfma_f32_16x16x32_bf16 v[74:77], v[58:61], v[228:231], v[74:77]
	v_mfma_f32_16x16x32_bf16 v[30:33], v[50:53], v[246:249], v[30:33]
	v_mfma_f32_16x16x32_bf16 v[26:29], v[58:61], v[246:249], v[26:29]
	v_mfma_f32_16x16x32_bf16 v[14:17], v[50:53], v[232:235], v[14:17]
	v_mfma_f32_16x16x32_bf16 v[10:13], v[58:61], v[232:235], v[10:13]
	v_mfma_f32_16x16x32_bf16 v[90:93], v[62:65], v[70:73], v[82:85]
	v_mfma_f32_16x16x32_bf16 v[78:81], v[54:57], v[242:245], v[78:81]
	v_mfma_f32_16x16x32_bf16 v[74:77], v[62:65], v[242:245], v[74:77]
	v_mfma_f32_16x16x32_bf16 v[30:33], v[54:57], v[250:253], v[30:33]
	v_mfma_f32_16x16x32_bf16 v[26:29], v[62:65], v[250:253], v[26:29]
	v_mfma_f32_16x16x32_bf16 v[14:17], v[54:57], v[236:239], v[14:17]
	v_mfma_f32_16x16x32_bf16 v[10:13], v[62:65], v[236:239], v[10:13]
	s_setprio 0
	s_setprio 1
	v_mfma_f32_16x16x32_bf16 v[34:37], v[172:175], v[66:69], v[34:37]
	v_mfma_f32_16x16x32_bf16 v[86:89], v[182:185], v[70:73], v[34:37]
	v_mfma_f32_16x16x32_bf16 v[34:37], v[220:223], v[66:69], v[38:41]
	v_mfma_f32_16x16x32_bf16 v[82:85], v[224:227], v[70:73], v[34:37]
	v_mfma_f32_16x16x32_bf16 v[34:37], v[172:175], v[228:231], v[42:45]
	v_mfma_f32_16x16x32_bf16 v[70:73], v[182:185], v[242:245], v[34:37]
	v_mfma_f32_16x16x32_bf16 v[34:37], v[220:223], v[228:231], v[46:49]
	v_mfma_f32_16x16x32_bf16 v[22:25], v[172:175], v[246:249], v[22:25]
	v_mfma_f32_16x16x32_bf16 v[18:21], v[220:223], v[246:249], v[18:21]
	v_mfma_f32_16x16x32_bf16 v[6:9], v[172:175], v[232:235], v[6:9]
	v_mfma_f32_16x16x32_bf16 v[2:5], v[220:223], v[232:235], v[2:5]
	v_mfma_f32_16x16x32_bf16 v[66:69], v[224:227], v[242:245], v[34:37]
	v_mfma_f32_16x16x32_bf16 v[22:25], v[182:185], v[250:253], v[22:25]
	v_mfma_f32_16x16x32_bf16 v[18:21], v[224:227], v[250:253], v[18:21]
	v_mfma_f32_16x16x32_bf16 v[6:9], v[182:185], v[236:239], v[6:9]
	v_mfma_f32_16x16x32_bf16 v[2:5], v[224:227], v[236:239], v[2:5]
	s_setprio 0
	s_barrier
	s_add_i32 s96, s96, 2
	s_add_u32 s40, s40, 0x100
	s_addc_u32 s41, s41, 0
	s_add_u32 s94, s94, 0x100
	s_addc_u32 s95, s95, 0
	s_cmp_gt_u32 s96, 13
	s_cbranch_scc0 .LBB0_1893
	v_mov_b32_e32 v173, v178
	v_mov_b32_e32 v177, v179
	s_lshl_b32 s2, s34, 8
	s_add_i32 s2, s2, s58
	v_add_u32_e32 v172, s2, v173
	s_lshl_b32 s2, s15, 8
	v_lshlrev_b32_e32 v173, 2, v173
	v_lshlrev_b32_e32 v174, 3, v177
	s_or_b32 s2, s2, s82
	v_lshl_add_u32 v173, v177, 6, v173
	v_add_u32_e32 v34, s2, v174
	s_lshl_b32 s2, s15, 7
	v_xor_b32_e32 v183, 64, v173
	v_xor_b32_e32 v182, 0x80, v173
	v_ashrrev_i32_e32 v173, 31, v172
	v_ashrrev_i32_e32 v35, 31, v34
	s_or_b32 s2, s2, s82
	v_ashrrev_i32_e32 v175, 31, v174
	v_lshlrev_b64 v[184:185], 7, v[172:173]
	v_lshlrev_b64 v[34:35], 2, v[34:35]
	v_add_u32_e32 v176, s2, v174
	v_lshl_add_u64 v[184:185], s[22:23], 0, v[184:185]
	v_lshlrev_b64 v[174:175], 2, v[174:175]
	v_lshl_add_u64 v[36:37], s[24:25], 0, v[34:35]
	v_lshl_add_u64 v[50:51], s[26:27], 0, v[34:35]
	v_lshl_add_u64 v[196:197], v[184:185], 0, v[174:175]
	global_load_dwordx4 v[46:49], v[36:37], off offset:16
	global_load_dwordx4 v[62:65], v[36:37], off
	global_load_dwordx4 v[42:45], v[50:51], off offset:16
	global_load_dwordx4 v[58:61], v[50:51], off
	global_load_dwordx4 v[38:41], v[36:37], off offset:528
	global_load_dwordx4 v[54:57], v[36:37], off offset:512
	s_nop 0
	global_load_dwordx4 v[34:37], v[50:51], off offset:528
	s_nop 0
	global_load_dwordx4 v[50:53], v[50:51], off offset:512
	s_nop 0
	global_load_dwordx4 v[184:187], v[196:197], off offset:16
	global_load_dwordx4 v[220:223], v[196:197], off
	s_and_b64 vcc, exec, s[28:29]
	s_cbranch_vccz .LBB0_1896
	s_barrier
; DI float bperm(float v, int srclane) { return __int_as_float(__builtin_amdgcn_ds_bpermute(srclane << 2, __float_as_int(v))); }
; DI unsigned pk2(float lo, float hi) { const f32x2 v = {lo, hi}; const hwbf16x2 b = __builtin_convertvector(v, hwbf16x2); return __builtin_bit_cast(unsigned, b); }
; DI float silu_f(float x) { return x * __builtin_amdgcn_rcpf(1.0f + __expf(-x)); }
; DI void row_stats(const float* STAT, int row, int fq, int lane, float& mu, float& rstd) {
;     const f32x4 a = *(const f32x4*)(STAT + (size_t)row * 32 + fq * 8), b = *(const f32x4*)(STAT + (size_t)row * 32 + fq * 8 + 4);
;     float s = (a[0] + a[2]) + (b[0] + b[2]), q = (a[1] + a[3]) + (b[1] + b[3]);
;     s += bperm(s, lane ^ 16); q += bperm(q, lane ^ 16); s += bperm(s, lane ^ 32); q += bperm(q, lane ^ 32);
;     mu = s * (1.0f / 1024.0f); rstd = __builtin_amdgcn_rsqf(fmaxf(q * (1.0f / 1024.0f) - mu * mu, 0.f) + EPS);
; }
;     DI void operator()(const f32x4 (&acc)[2][2][4][2], const pg8::Unit& u, int wr, int wc, int fr, int fq) const {
;     ...
;             for (int m = 0; m < 4; ++m) { const int row = row0 + ai * 128 + m * 16; float mu, rstd; row_stats(STAT, row, fq, lane, mu, rstd);
;                 const f32x4 g0 = (acc[ai][0][m][0] - c1[0][0] * mu) * rstd + c2[0][0], g1 = (acc[ai][0][m][1] - c1[0][1] * mu) * rstd + c2[0][1];
;                 const f32x4 u0 = (acc[ai][1][m][0] - c1[1][0] * mu) * rstd + c2[1][0], u1 = (acc[ai][1][m][1] - c1[1][1] * mu) * rstd + c2[1][1];
;                 u32x4 w; w.x = pk2(silu_f(g0[0]) * u0[0], silu_f(g0[1]) * u0[1]); w.y = pk2(silu_f(g0[2]) * u0[2], silu_f(g0[3]) * u0[3]);
;                 w.z = pk2(silu_f(g1[0]) * u1[0], silu_f(g1[1]) * u1[1]); w.w = pk2(silu_f(g1[2]) * u1[2], silu_f(g1[3]) * u1[3]);
;                 *(u32x4*)(HID + (size_t)row * DFF + col0) = w; }
.LBB0_1896:
	s_mov_b32 s34, 0x3a800000
	v_ashrrev_i32_e32 v177, 31, v176
	s_movk_i32 s15, 0x1600
	s_andn2_b64 vcc, exec, s[16:17]
	v_readlane_b32 s61, v254, 55
	s_waitcnt vmcnt(0)
	v_xor_b32_e32 v49, 0x80000000, v49
	v_xor_b32_e32 v48, 0x80000000, v48
	v_xor_b32_e32 v41, 0x80000000, v41
	v_xor_b32_e32 v40, 0x80000000, v40
	v_xor_b32_e32 v57, 0x80000000, v57
	v_pk_add_f32 v[184:185], v[184:185], v[186:187]
	v_pk_add_f32 v[196:197], v[220:221], v[222:223]
	v_xor_b32_e32 v56, 0x80000000, v56
	v_pk_add_f32 v[184:185], v[196:197], v[184:185]
	ds_bpermute_b32 v186, v183, v184
	ds_bpermute_b32 v187, v183, v185
	s_waitcnt lgkmcnt(0)
	v_pk_add_f32 v[184:185], v[184:185], v[186:187]
	ds_bpermute_b32 v186, v182, v184
	ds_bpermute_b32 v187, v182, v185
	s_waitcnt lgkmcnt(0)
	v_pk_add_f32 v[184:185], v[184:185], v[186:187]
	s_nop 0
	v_pk_mul_f32 v[184:185], v[184:185], s[34:35] op_sel_hi:[1,0]
	s_nop 0
	v_fma_f32 v173, -v184, v184, v185
	v_max_f32_e32 v173, 0, v173
	v_add_f32_e32 v173, 0x3727c5ac, v173
	v_rsq_f32_e32 v186, v173
	v_pk_fma_f32 v[196:197], v[62:63], v[184:185], v[158:159] op_sel_hi:[1,0,1] neg_lo:[1,0,0] neg_hi:[1,0,0]
	v_xor_b32_e32 v159, 0x80000000, v65
	v_xor_b32_e32 v158, 0x80000000, v64
	v_pk_fma_f32 v[64:65], v[158:159], v[184:185], v[160:161] op_sel_hi:[1,0,1]
	v_pk_fma_f32 v[160:161], v[196:197], v[186:187], v[58:59] op_sel_hi:[1,0,1]
	v_pk_fma_f32 v[146:147], v[38:39], v[184:185], v[146:147] op_sel_hi:[1,0,1] neg_lo:[1,0,0] neg_hi:[1,0,0]
	v_pk_fma_f32 v[148:149], v[40:41], v[184:185], v[148:149] op_sel_hi:[1,0,1]
	v_pk_fma_f32 v[154:155], v[46:47], v[184:185], v[154:155] op_sel_hi:[1,0,1] neg_lo:[1,0,0] neg_hi:[1,0,0]
	v_pk_fma_f32 v[156:157], v[48:49], v[184:185], v[156:157] op_sel_hi:[1,0,1]
	v_pk_fma_f32 v[150:151], v[54:55], v[184:185], v[150:151] op_sel_hi:[1,0,1] neg_lo:[1,0,0] neg_hi:[1,0,0]
	v_pk_fma_f32 v[152:153], v[56:57], v[184:185], v[152:153] op_sel_hi:[1,0,1]
	v_pk_fma_f32 v[184:185], v[148:149], v[186:187], v[36:37] op_sel_hi:[1,0,1]
	v_pk_fma_f32 v[148:149], v[146:147], v[186:187], v[34:35] op_sel_hi:[1,0,1]
	v_mul_f32_e32 v146, 0xbfb8aa3b, v160
	v_mul_f32_e32 v147, 0xbfb8aa3b, v161
	v_exp_f32_e32 v146, v146
	v_exp_f32_e32 v147, v147
	v_pk_fma_f32 v[150:151], v[150:151], v[186:187], v[50:51] op_sel_hi:[1,0,1]
	v_pk_fma_f32 v[64:65], v[64:65], v[186:187], v[60:61] op_sel_hi:[1,0,1]
	v_add_f32_e32 v146, 1.0, v146
	v_add_f32_e32 v147, 1.0, v147
	v_rcp_f32_e32 v146, v146
	v_rcp_f32_e32 v147, v147
	v_pk_fma_f32 v[152:153], v[152:153], v[186:187], v[52:53] op_sel_hi:[1,0,1]
	v_pk_fma_f32 v[154:155], v[154:155], v[186:187], v[42:43] op_sel_hi:[1,0,1]
	v_pk_fma_f32 v[156:157], v[156:157], v[186:187], v[44:45] op_sel_hi:[1,0,1]
	v_pk_mul_f32 v[146:147], v[160:161], v[146:147]
	s_nop 0
	v_pk_mul_f32 v[146:147], v[150:151], v[146:147]
	s_nop 0
	v_cvt_pk_bf16_f32 v146, v146, v147
	v_mul_f32_e32 v147, 0xbfb8aa3b, v64
	v_exp_f32_e32 v147, v147
	s_nop 0
	v_add_f32_e32 v147, 1.0, v147
	v_rcp_f32_e32 v150, v147
	v_mul_f32_e32 v147, 0xbfb8aa3b, v65
	v_exp_f32_e32 v147, v147
	s_nop 0
	v_add_f32_e32 v147, 1.0, v147
	v_rcp_f32_e32 v151, v147
	s_nop 0
	v_pk_mul_f32 v[64:65], v[64:65], v[150:151]
	s_nop 0
	v_pk_mul_f32 v[64:65], v[152:153], v[64:65]
	v_mov_b64_e32 v[150:151], s[20:21]
	v_cvt_pk_bf16_f32 v147, v64, v65
	v_mul_f32_e32 v64, 0xbfb8aa3b, v154
	v_mul_f32_e32 v65, 0xbfb8aa3b, v155
	v_exp_f32_e32 v64, v64
	v_exp_f32_e32 v65, v65
	v_lshlrev_b64 v[152:153], 1, v[176:177]
	v_add_f32_e32 v64, 1.0, v64
	v_add_f32_e32 v65, 1.0, v65
	v_rcp_f32_e32 v64, v64
	v_rcp_f32_e32 v65, v65
	s_nop 0
	v_pk_mul_f32 v[64:65], v[154:155], v[64:65]
	s_nop 0
	v_pk_mul_f32 v[64:65], v[148:149], v[64:65]
	s_nop 0
	v_cvt_pk_bf16_f32 v148, v64, v65
	v_mul_f32_e32 v64, 0xbfb8aa3b, v156
	v_mul_f32_e32 v65, 0xbfb8aa3b, v157
	v_exp_f32_e32 v64, v64
	v_exp_f32_e32 v65, v65
	v_add_f32_e32 v64, 1.0, v64
	v_add_f32_e32 v65, 1.0, v65
	v_rcp_f32_e32 v64, v64
	v_rcp_f32_e32 v65, v65
	s_nop 0
	v_pk_mul_f32 v[64:65], v[156:157], v[64:65]
	s_nop 0
	v_pk_mul_f32 v[64:65], v[184:185], v[64:65]
	s_nop 0
	v_cvt_pk_bf16_f32 v149, v64, v65
	v_mad_i64_i32 v[64:65], s[2:3], v172, s15, v[150:151]
	v_lshl_add_u64 v[64:65], v[64:65], 0, v[152:153]
	global_store_dwordx4 v[64:65], v[146:149], off
	v_add_u32_e32 v64, 16, v172
	v_ashrrev_i32_e32 v65, 31, v64
	v_lshlrev_b64 v[146:147], 7, v[64:65]
	v_lshl_add_u64 v[146:147], s[22:23], 0, v[146:147]
	v_lshl_add_u64 v[154:155], v[146:147], 0, v[174:175]
	global_load_dwordx4 v[146:149], v[154:155], off offset:16
	s_nop 0
	global_load_dwordx4 v[154:157], v[154:155], off
	s_waitcnt vmcnt(1)
	v_pk_add_f32 v[146:147], v[146:147], v[148:149]
	s_waitcnt vmcnt(0)
	v_pk_add_f32 v[154:155], v[154:155], v[156:157]
	s_nop 0
	v_pk_add_f32 v[146:147], v[154:155], v[146:147]
	ds_bpermute_b32 v148, v183, v146
	ds_bpermute_b32 v149, v183, v147
	s_waitcnt lgkmcnt(0)
	v_pk_add_f32 v[146:147], v[146:147], v[148:149]
	ds_bpermute_b32 v148, v182, v146
	ds_bpermute_b32 v149, v182, v147
	s_waitcnt lgkmcnt(0)
; DI float bperm(float v, int srclane) { return __int_as_float(__builtin_amdgcn_ds_bpermute(srclane << 2, __float_as_int(v))); }
; DI unsigned pk2(float lo, float hi) { const f32x2 v = {lo, hi}; const hwbf16x2 b = __builtin_convertvector(v, hwbf16x2); return __builtin_bit_cast(unsigned, b); }
; DI float silu_f(float x) { return x * __builtin_amdgcn_rcpf(1.0f + __expf(-x)); }
; DI void row_stats(const float* STAT, int row, int fq, int lane, float& mu, float& rstd) {
;     const f32x4 a = *(const f32x4*)(STAT + (size_t)row * 32 + fq * 8), b = *(const f32x4*)(STAT + (size_t)row * 32 + fq * 8 + 4);
;     float s = (a[0] + a[2]) + (b[0] + b[2]), q = (a[1] + a[3]) + (b[1] + b[3]);
;     s += bperm(s, lane ^ 16); q += bperm(q, lane ^ 16); s += bperm(s, lane ^ 32); q += bperm(q, lane ^ 32);
;     mu = s * (1.0f / 1024.0f); rstd = __builtin_amdgcn_rsqf(fmaxf(q * (1.0f / 1024.0f) - mu * mu, 0.f) + EPS);
; }
;     DI void operator()(const f32x4 (&acc)[2][2][4][2], const pg8::Unit& u, int wr, int wc, int fr, int fq) const {
;     ...
;             for (int m = 0; m < 4; ++m) { const int row = row0 + ai * 128 + m * 16; float mu, rstd; row_stats(STAT, row, fq, lane, mu, rstd);
;                 const f32x4 g0 = (acc[ai][0][m][0] - c1[0][0] * mu) * rstd + c2[0][0], g1 = (acc[ai][0][m][1] - c1[0][1] * mu) * rstd + c2[0][1];
;                 const f32x4 u0 = (acc[ai][1][m][0] - c1[1][0] * mu) * rstd + c2[1][0], u1 = (acc[ai][1][m][1] - c1[1][1] * mu) * rstd + c2[1][1];
;                 u32x4 w; w.x = pk2(silu_f(g0[0]) * u0[0], silu_f(g0[1]) * u0[1]); w.y = pk2(silu_f(g0[2]) * u0[2], silu_f(g0[3]) * u0[3]);
;                 w.z = pk2(silu_f(g1[0]) * u1[0], silu_f(g1[1]) * u1[1]); w.w = pk2(silu_f(g1[2]) * u1[2], silu_f(g1[3]) * u1[3]);
;                 *(u32x4*)(HID + (size_t)row * DFF + col0) = w; }
	v_pk_add_f32 v[146:147], v[146:147], v[148:149]
	s_nop 0
	v_pk_mul_f32 v[146:147], v[146:147], s[34:35] op_sel_hi:[1,0]
	s_nop 0
	v_fma_f32 v65, -v146, v146, v147
	v_max_f32_e32 v65, 0, v65
	v_add_f32_e32 v65, 0x3727c5ac, v65
	v_rsq_f32_e32 v148, v65
	v_pk_fma_f32 v[142:143], v[62:63], v[146:147], v[142:143] op_sel_hi:[1,0,1] neg_lo:[1,0,0] neg_hi:[1,0,0]
	v_pk_fma_f32 v[130:131], v[38:39], v[146:147], v[130:131] op_sel_hi:[1,0,1] neg_lo:[1,0,0] neg_hi:[1,0,0]
	v_pk_fma_f32 v[132:133], v[40:41], v[146:147], v[132:133] op_sel_hi:[1,0,1]
	v_pk_fma_f32 v[142:143], v[142:143], v[148:149], v[58:59] op_sel_hi:[1,0,1]
	v_pk_fma_f32 v[144:145], v[158:159], v[146:147], v[144:145] op_sel_hi:[1,0,1]
	v_mul_f32_e32 v65, 0xbfb8aa3b, v142
	v_exp_f32_e32 v65, v65
	v_pk_fma_f32 v[138:139], v[46:47], v[146:147], v[138:139] op_sel_hi:[1,0,1] neg_lo:[1,0,0] neg_hi:[1,0,0]
	v_pk_fma_f32 v[140:141], v[48:49], v[146:147], v[140:141] op_sel_hi:[1,0,1]
	v_pk_fma_f32 v[134:135], v[54:55], v[146:147], v[134:135] op_sel_hi:[1,0,1] neg_lo:[1,0,0] neg_hi:[1,0,0]
	v_add_f32_e32 v65, 1.0, v65
	v_pk_fma_f32 v[136:137], v[56:57], v[146:147], v[136:137] op_sel_hi:[1,0,1]
	v_pk_fma_f32 v[146:147], v[132:133], v[148:149], v[36:37] op_sel_hi:[1,0,1]
	v_pk_fma_f32 v[132:133], v[130:131], v[148:149], v[34:35] op_sel_hi:[1,0,1]
	v_rcp_f32_e32 v130, v65
	v_mul_f32_e32 v65, 0xbfb8aa3b, v143
	v_exp_f32_e32 v65, v65
	v_pk_fma_f32 v[144:145], v[144:145], v[148:149], v[60:61] op_sel_hi:[1,0,1]
	v_pk_fma_f32 v[134:135], v[134:135], v[148:149], v[50:51] op_sel_hi:[1,0,1]
	v_pk_fma_f32 v[138:139], v[138:139], v[148:149], v[42:43] op_sel_hi:[1,0,1]
	v_add_f32_e32 v65, 1.0, v65
	v_rcp_f32_e32 v131, v65
	v_mul_f32_e32 v65, 0xbfb8aa3b, v144
	v_exp_f32_e32 v65, v65
	v_pk_fma_f32 v[136:137], v[136:137], v[148:149], v[52:53] op_sel_hi:[1,0,1]
	v_pk_mul_f32 v[130:131], v[142:143], v[130:131]
	v_pk_fma_f32 v[140:141], v[140:141], v[148:149], v[44:45] op_sel_hi:[1,0,1]
	v_add_f32_e32 v65, 1.0, v65
	v_pk_mul_f32 v[130:131], v[134:135], v[130:131]
	v_rcp_f32_e32 v134, v65
	v_mul_f32_e32 v65, 0xbfb8aa3b, v145
	v_exp_f32_e32 v65, v65
	v_cvt_pk_bf16_f32 v130, v130, v131
	v_add_f32_e32 v65, 1.0, v65
	v_rcp_f32_e32 v135, v65
	v_mul_f32_e32 v65, 0xbfb8aa3b, v138
	v_exp_f32_e32 v65, v65
	v_pk_mul_f32 v[134:135], v[144:145], v[134:135]
	s_nop 0
	v_pk_mul_f32 v[134:135], v[136:137], v[134:135]
	v_add_f32_e32 v65, 1.0, v65
	v_cvt_pk_bf16_f32 v131, v134, v135
	v_rcp_f32_e32 v134, v65
	v_mul_f32_e32 v65, 0xbfb8aa3b, v139
	v_exp_f32_e32 v65, v65
	s_nop 0
	v_add_f32_e32 v65, 1.0, v65
	v_rcp_f32_e32 v135, v65
	v_mul_f32_e32 v65, 0xbfb8aa3b, v140
	v_exp_f32_e32 v65, v65
	v_pk_mul_f32 v[134:135], v[138:139], v[134:135]
	s_nop 0
	v_pk_mul_f32 v[132:133], v[132:133], v[134:135]
	v_add_f32_e32 v65, 1.0, v65
	v_rcp_f32_e32 v134, v65
	v_mul_f32_e32 v65, 0xbfb8aa3b, v141
	v_exp_f32_e32 v65, v65
	v_cvt_pk_bf16_f32 v132, v132, v133
	v_add_f32_e32 v65, 1.0, v65
	v_rcp_f32_e32 v135, v65
	v_mad_i64_i32 v[64:65], s[2:3], v64, s15, v[150:151]
	v_lshl_add_u64 v[64:65], v[64:65], 0, v[152:153]
	v_pk_mul_f32 v[134:135], v[140:141], v[134:135]
	s_nop 0
	v_pk_mul_f32 v[134:135], v[146:147], v[134:135]
	s_nop 0
	v_cvt_pk_bf16_f32 v133, v134, v135
	global_store_dwordx4 v[64:65], v[130:133], off
	v_add_u32_e32 v64, 32, v172
	v_ashrrev_i32_e32 v65, 31, v64
	v_lshlrev_b64 v[130:131], 7, v[64:65]
	v_lshl_add_u64 v[130:131], s[22:23], 0, v[130:131]
	v_lshl_add_u64 v[134:135], v[130:131], 0, v[174:175]
	global_load_dwordx4 v[130:133], v[134:135], off offset:16
	s_nop 0
	global_load_dwordx4 v[134:137], v[134:135], off
	s_waitcnt vmcnt(1)
	v_pk_add_f32 v[130:131], v[130:131], v[132:133]
	s_waitcnt vmcnt(0)
	v_pk_add_f32 v[134:135], v[134:135], v[136:137]
	s_nop 0
	v_pk_add_f32 v[130:131], v[134:135], v[130:131]
	ds_bpermute_b32 v132, v183, v130
	ds_bpermute_b32 v133, v183, v131
	s_waitcnt lgkmcnt(0)
	v_pk_add_f32 v[130:131], v[130:131], v[132:133]
	ds_bpermute_b32 v132, v182, v130
	ds_bpermute_b32 v133, v182, v131
	s_waitcnt lgkmcnt(0)
	v_pk_add_f32 v[130:131], v[130:131], v[132:133]
	s_nop 0
	v_pk_mul_f32 v[130:131], v[130:131], s[34:35] op_sel_hi:[1,0]
	s_nop 0
	v_fma_f32 v65, -v130, v130, v131
	v_max_f32_e32 v65, 0, v65
	v_add_f32_e32 v65, 0x3727c5ac, v65
	v_rsq_f32_e32 v132, v65
	v_pk_fma_f32 v[126:127], v[62:63], v[130:131], v[126:127] op_sel_hi:[1,0,1] neg_lo:[1,0,0] neg_hi:[1,0,0]
	v_pk_fma_f32 v[114:115], v[38:39], v[130:131], v[114:115] op_sel_hi:[1,0,1] neg_lo:[1,0,0] neg_hi:[1,0,0]
	v_pk_fma_f32 v[116:117], v[40:41], v[130:131], v[116:117] op_sel_hi:[1,0,1]
	v_pk_fma_f32 v[126:127], v[126:127], v[132:133], v[58:59] op_sel_hi:[1,0,1]
	v_pk_fma_f32 v[128:129], v[158:159], v[130:131], v[128:129] op_sel_hi:[1,0,1]
	v_mul_f32_e32 v65, 0xbfb8aa3b, v126
	v_exp_f32_e32 v65, v65
	v_pk_fma_f32 v[122:123], v[46:47], v[130:131], v[122:123] op_sel_hi:[1,0,1] neg_lo:[1,0,0] neg_hi:[1,0,0]
	v_pk_fma_f32 v[124:125], v[48:49], v[130:131], v[124:125] op_sel_hi:[1,0,1]
	v_pk_fma_f32 v[118:119], v[54:55], v[130:131], v[118:119] op_sel_hi:[1,0,1] neg_lo:[1,0,0] neg_hi:[1,0,0]
	v_add_f32_e32 v65, 1.0, v65
	v_pk_fma_f32 v[120:121], v[56:57], v[130:131], v[120:121] op_sel_hi:[1,0,1]
	v_pk_fma_f32 v[130:131], v[116:117], v[132:133], v[36:37] op_sel_hi:[1,0,1]
	v_pk_fma_f32 v[116:117], v[114:115], v[132:133], v[34:35] op_sel_hi:[1,0,1]
	v_rcp_f32_e32 v114, v65
	v_mul_f32_e32 v65, 0xbfb8aa3b, v127
	v_exp_f32_e32 v65, v65
	v_pk_fma_f32 v[128:129], v[128:129], v[132:133], v[60:61] op_sel_hi:[1,0,1]
	v_pk_fma_f32 v[118:119], v[118:119], v[132:133], v[50:51] op_sel_hi:[1,0,1]
	v_pk_fma_f32 v[122:123], v[122:123], v[132:133], v[42:43] op_sel_hi:[1,0,1]
; DI float bperm(float v, int srclane) { return __int_as_float(__builtin_amdgcn_ds_bpermute(srclane << 2, __float_as_int(v))); }
; DI unsigned pk2(float lo, float hi) { const f32x2 v = {lo, hi}; const hwbf16x2 b = __builtin_convertvector(v, hwbf16x2); return __builtin_bit_cast(unsigned, b); }
; DI float silu_f(float x) { return x * __builtin_amdgcn_rcpf(1.0f + __expf(-x)); }
; DI void row_stats(const float* STAT, int row, int fq, int lane, float& mu, float& rstd) {
;     const f32x4 a = *(const f32x4*)(STAT + (size_t)row * 32 + fq * 8), b = *(const f32x4*)(STAT + (size_t)row * 32 + fq * 8 + 4);
;     float s = (a[0] + a[2]) + (b[0] + b[2]), q = (a[1] + a[3]) + (b[1] + b[3]);
;     s += bperm(s, lane ^ 16); q += bperm(q, lane ^ 16); s += bperm(s, lane ^ 32); q += bperm(q, lane ^ 32);
;     mu = s * (1.0f / 1024.0f); rstd = __builtin_amdgcn_rsqf(fmaxf(q * (1.0f / 1024.0f) - mu * mu, 0.f) + EPS);
; }
;     DI void operator()(const f32x4 (&acc)[2][2][4][2], const pg8::Unit& u, int wr, int wc, int fr, int fq) const {
;     ...
;             for (int m = 0; m < 4; ++m) { const int row = row0 + ai * 128 + m * 16; float mu, rstd; row_stats(STAT, row, fq, lane, mu, rstd);
;                 const f32x4 g0 = (acc[ai][0][m][0] - c1[0][0] * mu) * rstd + c2[0][0], g1 = (acc[ai][0][m][1] - c1[0][1] * mu) * rstd + c2[0][1];
;                 const f32x4 u0 = (acc[ai][1][m][0] - c1[1][0] * mu) * rstd + c2[1][0], u1 = (acc[ai][1][m][1] - c1[1][1] * mu) * rstd + c2[1][1];
;                 u32x4 w; w.x = pk2(silu_f(g0[0]) * u0[0], silu_f(g0[1]) * u0[1]); w.y = pk2(silu_f(g0[2]) * u0[2], silu_f(g0[3]) * u0[3]);
;                 w.z = pk2(silu_f(g1[0]) * u1[0], silu_f(g1[1]) * u1[1]); w.w = pk2(silu_f(g1[2]) * u1[2], silu_f(g1[3]) * u1[3]);
;                 *(u32x4*)(HID + (size_t)row * DFF + col0) = w; }
	v_add_f32_e32 v65, 1.0, v65
	v_rcp_f32_e32 v115, v65
	v_mul_f32_e32 v65, 0xbfb8aa3b, v128
	v_exp_f32_e32 v65, v65
	v_pk_fma_f32 v[120:121], v[120:121], v[132:133], v[52:53] op_sel_hi:[1,0,1]
	v_pk_mul_f32 v[114:115], v[126:127], v[114:115]
	v_pk_fma_f32 v[124:125], v[124:125], v[132:133], v[44:45] op_sel_hi:[1,0,1]
	v_add_f32_e32 v65, 1.0, v65
	v_pk_mul_f32 v[114:115], v[118:119], v[114:115]
	v_rcp_f32_e32 v118, v65
	v_mul_f32_e32 v65, 0xbfb8aa3b, v129
	v_exp_f32_e32 v65, v65
	v_cvt_pk_bf16_f32 v114, v114, v115
	v_add_f32_e32 v65, 1.0, v65
	v_rcp_f32_e32 v119, v65
	v_mul_f32_e32 v65, 0xbfb8aa3b, v122
	v_exp_f32_e32 v65, v65
	v_pk_mul_f32 v[118:119], v[128:129], v[118:119]
	s_nop 0
	v_pk_mul_f32 v[118:119], v[120:121], v[118:119]
	v_add_f32_e32 v65, 1.0, v65
	v_cvt_pk_bf16_f32 v115, v118, v119
	v_rcp_f32_e32 v118, v65
	v_mul_f32_e32 v65, 0xbfb8aa3b, v123
	v_exp_f32_e32 v65, v65
	s_nop 0
	v_add_f32_e32 v65, 1.0, v65
	v_rcp_f32_e32 v119, v65
	v_mul_f32_e32 v65, 0xbfb8aa3b, v124
	v_exp_f32_e32 v65, v65
	v_pk_mul_f32 v[118:119], v[122:123], v[118:119]
	s_nop 0
	v_pk_mul_f32 v[116:117], v[116:117], v[118:119]
	v_add_f32_e32 v65, 1.0, v65
	v_rcp_f32_e32 v118, v65
	v_mul_f32_e32 v65, 0xbfb8aa3b, v125
	v_exp_f32_e32 v65, v65
	v_cvt_pk_bf16_f32 v116, v116, v117
	v_add_f32_e32 v65, 1.0, v65
	v_rcp_f32_e32 v119, v65
	v_mad_i64_i32 v[64:65], s[2:3], v64, s15, v[150:151]
	v_lshl_add_u64 v[64:65], v[64:65], 0, v[152:153]
	v_pk_mul_f32 v[118:119], v[124:125], v[118:119]
	s_nop 0
	v_pk_mul_f32 v[118:119], v[130:131], v[118:119]
	s_nop 0
	v_cvt_pk_bf16_f32 v117, v118, v119
	global_store_dwordx4 v[64:65], v[114:117], off
	v_add_u32_e32 v64, 48, v172
	v_ashrrev_i32_e32 v65, 31, v64
	v_lshlrev_b64 v[114:115], 7, v[64:65]
	v_lshl_add_u64 v[114:115], s[22:23], 0, v[114:115]
	v_lshl_add_u64 v[118:119], v[114:115], 0, v[174:175]
	global_load_dwordx4 v[114:117], v[118:119], off offset:16
	s_nop 0
	global_load_dwordx4 v[118:121], v[118:119], off
	s_waitcnt vmcnt(1)
	v_pk_add_f32 v[114:115], v[114:115], v[116:117]
	s_waitcnt vmcnt(0)
	v_pk_add_f32 v[118:119], v[118:119], v[120:121]
	s_nop 0
	v_pk_add_f32 v[114:115], v[118:119], v[114:115]
	ds_bpermute_b32 v116, v183, v114
	ds_bpermute_b32 v117, v183, v115
	s_waitcnt lgkmcnt(0)
	v_pk_add_f32 v[114:115], v[114:115], v[116:117]
	ds_bpermute_b32 v116, v182, v114
	ds_bpermute_b32 v117, v182, v115
	s_waitcnt lgkmcnt(0)
	v_pk_add_f32 v[114:115], v[114:115], v[116:117]
	s_nop 0
	v_pk_mul_f32 v[114:115], v[114:115], s[34:35] op_sel_hi:[1,0]
	s_nop 0
	v_fma_f32 v65, -v114, v114, v115
	v_max_f32_e32 v65, 0, v65
	v_add_f32_e32 v65, 0x3727c5ac, v65
	v_rsq_f32_e32 v116, v65
	v_pk_fma_f32 v[110:111], v[62:63], v[114:115], v[110:111] op_sel_hi:[1,0,1] neg_lo:[1,0,0] neg_hi:[1,0,0]
	v_pk_fma_f32 v[98:99], v[38:39], v[114:115], v[98:99] op_sel_hi:[1,0,1] neg_lo:[1,0,0] neg_hi:[1,0,0]
	v_pk_fma_f32 v[100:101], v[40:41], v[114:115], v[100:101] op_sel_hi:[1,0,1]
	v_pk_fma_f32 v[110:111], v[110:111], v[116:117], v[58:59] op_sel_hi:[1,0,1]
	v_pk_fma_f32 v[112:113], v[158:159], v[114:115], v[112:113] op_sel_hi:[1,0,1]
	v_mul_f32_e32 v65, 0xbfb8aa3b, v110
	v_exp_f32_e32 v65, v65
	v_pk_fma_f32 v[106:107], v[46:47], v[114:115], v[106:107] op_sel_hi:[1,0,1] neg_lo:[1,0,0] neg_hi:[1,0,0]
	v_pk_fma_f32 v[108:109], v[48:49], v[114:115], v[108:109] op_sel_hi:[1,0,1]
	v_pk_fma_f32 v[102:103], v[54:55], v[114:115], v[102:103] op_sel_hi:[1,0,1] neg_lo:[1,0,0] neg_hi:[1,0,0]
	v_add_f32_e32 v65, 1.0, v65
	v_pk_fma_f32 v[104:105], v[56:57], v[114:115], v[104:105] op_sel_hi:[1,0,1]
	v_pk_fma_f32 v[114:115], v[100:101], v[116:117], v[36:37] op_sel_hi:[1,0,1]
	v_pk_fma_f32 v[100:101], v[98:99], v[116:117], v[34:35] op_sel_hi:[1,0,1]
	v_rcp_f32_e32 v98, v65
	v_mul_f32_e32 v65, 0xbfb8aa3b, v111
	v_exp_f32_e32 v65, v65
	v_pk_fma_f32 v[112:113], v[112:113], v[116:117], v[60:61] op_sel_hi:[1,0,1]
	v_pk_fma_f32 v[102:103], v[102:103], v[116:117], v[50:51] op_sel_hi:[1,0,1]
	v_pk_fma_f32 v[106:107], v[106:107], v[116:117], v[42:43] op_sel_hi:[1,0,1]
	v_add_f32_e32 v65, 1.0, v65
	v_rcp_f32_e32 v99, v65
	v_mul_f32_e32 v65, 0xbfb8aa3b, v112
	v_exp_f32_e32 v65, v65
	v_pk_fma_f32 v[104:105], v[104:105], v[116:117], v[52:53] op_sel_hi:[1,0,1]
	v_pk_mul_f32 v[98:99], v[110:111], v[98:99]
	v_pk_fma_f32 v[108:109], v[108:109], v[116:117], v[44:45] op_sel_hi:[1,0,1]
	v_add_f32_e32 v65, 1.0, v65
	v_pk_mul_f32 v[98:99], v[102:103], v[98:99]
	v_rcp_f32_e32 v102, v65
	v_mul_f32_e32 v65, 0xbfb8aa3b, v113
	v_exp_f32_e32 v65, v65
	v_cvt_pk_bf16_f32 v98, v98, v99
	v_add_f32_e32 v65, 1.0, v65
	v_rcp_f32_e32 v103, v65
	v_mul_f32_e32 v65, 0xbfb8aa3b, v106
	v_exp_f32_e32 v65, v65
	v_pk_mul_f32 v[102:103], v[112:113], v[102:103]
	s_nop 0
	v_pk_mul_f32 v[102:103], v[104:105], v[102:103]
	v_add_f32_e32 v65, 1.0, v65
	v_cvt_pk_bf16_f32 v99, v102, v103
	v_rcp_f32_e32 v102, v65
	v_mul_f32_e32 v65, 0xbfb8aa3b, v107
	v_exp_f32_e32 v65, v65
	s_nop 0
	v_add_f32_e32 v65, 1.0, v65
	v_rcp_f32_e32 v103, v65
	v_mul_f32_e32 v65, 0xbfb8aa3b, v108
	v_exp_f32_e32 v65, v65
	v_pk_mul_f32 v[102:103], v[106:107], v[102:103]
	s_nop 0
	v_pk_mul_f32 v[100:101], v[100:101], v[102:103]
	v_add_f32_e32 v65, 1.0, v65
	v_rcp_f32_e32 v102, v65
	v_mul_f32_e32 v65, 0xbfb8aa3b, v109
	v_exp_f32_e32 v65, v65
	v_cvt_pk_bf16_f32 v100, v100, v101
	v_add_f32_e32 v65, 1.0, v65
	v_rcp_f32_e32 v103, v65
	v_mad_i64_i32 v[64:65], s[2:3], v64, s15, v[150:151]
	v_lshl_add_u64 v[64:65], v[64:65], 0, v[152:153]
	v_pk_mul_f32 v[102:103], v[108:109], v[102:103]
	s_nop 0
	v_pk_mul_f32 v[102:103], v[114:115], v[102:103]
	s_nop 0
	v_cvt_pk_bf16_f32 v101, v102, v103
	global_store_dwordx4 v[64:65], v[98:101], off
	v_add_u32_e32 v64, 0x80, v172
	v_ashrrev_i32_e32 v65, 31, v64
	v_lshlrev_b64 v[98:99], 7, v[64:65]
	v_lshl_add_u64 v[98:99], s[22:23], 0, v[98:99]
	v_lshl_add_u64 v[102:103], v[98:99], 0, v[174:175]
	global_load_dwordx4 v[98:101], v[102:103], off offset:16
	s_nop 0
	global_load_dwordx4 v[102:105], v[102:103], off
	s_waitcnt vmcnt(1)
; DI float bperm(float v, int srclane) { return __int_as_float(__builtin_amdgcn_ds_bpermute(srclane << 2, __float_as_int(v))); }
; DI unsigned pk2(float lo, float hi) { const f32x2 v = {lo, hi}; const hwbf16x2 b = __builtin_convertvector(v, hwbf16x2); return __builtin_bit_cast(unsigned, b); }
; DI float silu_f(float x) { return x * __builtin_amdgcn_rcpf(1.0f + __expf(-x)); }
; DI void row_stats(const float* STAT, int row, int fq, int lane, float& mu, float& rstd) {
;     const f32x4 a = *(const f32x4*)(STAT + (size_t)row * 32 + fq * 8), b = *(const f32x4*)(STAT + (size_t)row * 32 + fq * 8 + 4);
;     float s = (a[0] + a[2]) + (b[0] + b[2]), q = (a[1] + a[3]) + (b[1] + b[3]);
;     s += bperm(s, lane ^ 16); q += bperm(q, lane ^ 16); s += bperm(s, lane ^ 32); q += bperm(q, lane ^ 32);
;     mu = s * (1.0f / 1024.0f); rstd = __builtin_amdgcn_rsqf(fmaxf(q * (1.0f / 1024.0f) - mu * mu, 0.f) + EPS);
; }
;     DI void operator()(const f32x4 (&acc)[2][2][4][2], const pg8::Unit& u, int wr, int wc, int fr, int fq) const {
;     ...
;             for (int m = 0; m < 4; ++m) { const int row = row0 + ai * 128 + m * 16; float mu, rstd; row_stats(STAT, row, fq, lane, mu, rstd);
;                 const f32x4 g0 = (acc[ai][0][m][0] - c1[0][0] * mu) * rstd + c2[0][0], g1 = (acc[ai][0][m][1] - c1[0][1] * mu) * rstd + c2[0][1];
;                 const f32x4 u0 = (acc[ai][1][m][0] - c1[1][0] * mu) * rstd + c2[1][0], u1 = (acc[ai][1][m][1] - c1[1][1] * mu) * rstd + c2[1][1];
;                 u32x4 w; w.x = pk2(silu_f(g0[0]) * u0[0], silu_f(g0[1]) * u0[1]); w.y = pk2(silu_f(g0[2]) * u0[2], silu_f(g0[3]) * u0[3]);
;                 w.z = pk2(silu_f(g1[0]) * u1[0], silu_f(g1[1]) * u1[1]); w.w = pk2(silu_f(g1[2]) * u1[2], silu_f(g1[3]) * u1[3]);
;                 *(u32x4*)(HID + (size_t)row * DFF + col0) = w; }
	v_pk_add_f32 v[98:99], v[98:99], v[100:101]
	s_waitcnt vmcnt(0)
	v_pk_add_f32 v[102:103], v[102:103], v[104:105]
	s_nop 0
	v_pk_add_f32 v[98:99], v[102:103], v[98:99]
	ds_bpermute_b32 v100, v183, v98
	ds_bpermute_b32 v101, v183, v99
	s_waitcnt lgkmcnt(0)
	v_pk_add_f32 v[98:99], v[98:99], v[100:101]
	ds_bpermute_b32 v100, v182, v98
	ds_bpermute_b32 v101, v182, v99
	s_waitcnt lgkmcnt(0)
	v_pk_add_f32 v[98:99], v[98:99], v[100:101]
	s_nop 0
	v_pk_mul_f32 v[98:99], v[98:99], s[34:35] op_sel_hi:[1,0]
	s_nop 0
	v_fma_f32 v65, -v98, v98, v99
	v_max_f32_e32 v65, 0, v65
	v_add_f32_e32 v65, 0x3727c5ac, v65
	v_rsq_f32_e32 v100, v65
	v_pk_fma_f32 v[94:95], v[62:63], v[98:99], v[94:95] op_sel_hi:[1,0,1] neg_lo:[1,0,0] neg_hi:[1,0,0]
	v_pk_fma_f32 v[82:83], v[38:39], v[98:99], v[82:83] op_sel_hi:[1,0,1] neg_lo:[1,0,0] neg_hi:[1,0,0]
	v_pk_fma_f32 v[84:85], v[40:41], v[98:99], v[84:85] op_sel_hi:[1,0,1]
	v_pk_fma_f32 v[94:95], v[94:95], v[100:101], v[58:59] op_sel_hi:[1,0,1]
	v_pk_fma_f32 v[96:97], v[158:159], v[98:99], v[96:97] op_sel_hi:[1,0,1]
	v_mul_f32_e32 v65, 0xbfb8aa3b, v94
	v_exp_f32_e32 v65, v65
	v_pk_fma_f32 v[90:91], v[46:47], v[98:99], v[90:91] op_sel_hi:[1,0,1] neg_lo:[1,0,0] neg_hi:[1,0,0]
	v_pk_fma_f32 v[92:93], v[48:49], v[98:99], v[92:93] op_sel_hi:[1,0,1]
	v_pk_fma_f32 v[86:87], v[54:55], v[98:99], v[86:87] op_sel_hi:[1,0,1] neg_lo:[1,0,0] neg_hi:[1,0,0]
	v_add_f32_e32 v65, 1.0, v65
	v_pk_fma_f32 v[88:89], v[56:57], v[98:99], v[88:89] op_sel_hi:[1,0,1]
	v_pk_fma_f32 v[98:99], v[84:85], v[100:101], v[36:37] op_sel_hi:[1,0,1]
	v_pk_fma_f32 v[84:85], v[82:83], v[100:101], v[34:35] op_sel_hi:[1,0,1]
	v_rcp_f32_e32 v82, v65
	v_mul_f32_e32 v65, 0xbfb8aa3b, v95
	v_exp_f32_e32 v65, v65
	v_pk_fma_f32 v[96:97], v[96:97], v[100:101], v[60:61] op_sel_hi:[1,0,1]
	v_pk_fma_f32 v[86:87], v[86:87], v[100:101], v[50:51] op_sel_hi:[1,0,1]
	v_pk_fma_f32 v[90:91], v[90:91], v[100:101], v[42:43] op_sel_hi:[1,0,1]
	v_add_f32_e32 v65, 1.0, v65
	v_rcp_f32_e32 v83, v65
	v_mul_f32_e32 v65, 0xbfb8aa3b, v96
	v_exp_f32_e32 v65, v65
	v_pk_fma_f32 v[88:89], v[88:89], v[100:101], v[52:53] op_sel_hi:[1,0,1]
	v_pk_mul_f32 v[82:83], v[94:95], v[82:83]
	v_pk_fma_f32 v[92:93], v[92:93], v[100:101], v[44:45] op_sel_hi:[1,0,1]
	v_add_f32_e32 v65, 1.0, v65
	v_pk_mul_f32 v[82:83], v[86:87], v[82:83]
	v_rcp_f32_e32 v86, v65
	v_mul_f32_e32 v65, 0xbfb8aa3b, v97
	v_exp_f32_e32 v65, v65
	v_cvt_pk_bf16_f32 v82, v82, v83
	v_add_f32_e32 v65, 1.0, v65
	v_rcp_f32_e32 v87, v65
	v_mul_f32_e32 v65, 0xbfb8aa3b, v90
	v_exp_f32_e32 v65, v65
	v_pk_mul_f32 v[86:87], v[96:97], v[86:87]
	s_nop 0
	v_pk_mul_f32 v[86:87], v[88:89], v[86:87]
	v_add_f32_e32 v65, 1.0, v65
	v_cvt_pk_bf16_f32 v83, v86, v87
	v_rcp_f32_e32 v86, v65
	v_mul_f32_e32 v65, 0xbfb8aa3b, v91
	v_exp_f32_e32 v65, v65
	s_nop 0
	v_add_f32_e32 v65, 1.0, v65
	v_rcp_f32_e32 v87, v65
	v_mul_f32_e32 v65, 0xbfb8aa3b, v92
	v_exp_f32_e32 v65, v65
	v_pk_mul_f32 v[86:87], v[90:91], v[86:87]
	s_nop 0
	v_pk_mul_f32 v[84:85], v[84:85], v[86:87]
	v_add_f32_e32 v65, 1.0, v65
	v_rcp_f32_e32 v86, v65
	v_mul_f32_e32 v65, 0xbfb8aa3b, v93
	v_exp_f32_e32 v65, v65
	v_cvt_pk_bf16_f32 v84, v84, v85
	v_add_f32_e32 v65, 1.0, v65
	v_rcp_f32_e32 v87, v65
	v_mad_i64_i32 v[64:65], s[2:3], v64, s15, v[150:151]
	v_lshl_add_u64 v[64:65], v[64:65], 0, v[152:153]
	v_pk_mul_f32 v[86:87], v[92:93], v[86:87]
	s_nop 0
	v_pk_mul_f32 v[86:87], v[98:99], v[86:87]
	s_nop 0
	v_cvt_pk_bf16_f32 v85, v86, v87
	global_store_dwordx4 v[64:65], v[82:85], off
	v_add_u32_e32 v64, 0x90, v172
	v_ashrrev_i32_e32 v65, 31, v64
	v_lshlrev_b64 v[82:83], 7, v[64:65]
	v_lshl_add_u64 v[82:83], s[22:23], 0, v[82:83]
	v_lshl_add_u64 v[86:87], v[82:83], 0, v[174:175]
	global_load_dwordx4 v[82:85], v[86:87], off offset:16
	s_nop 0
	global_load_dwordx4 v[86:89], v[86:87], off
	s_waitcnt vmcnt(1)
	v_pk_add_f32 v[82:83], v[82:83], v[84:85]
	s_waitcnt vmcnt(0)
	v_pk_add_f32 v[86:87], v[86:87], v[88:89]
	s_nop 0
	v_pk_add_f32 v[82:83], v[86:87], v[82:83]
	ds_bpermute_b32 v84, v183, v82
	ds_bpermute_b32 v85, v183, v83
	s_waitcnt lgkmcnt(0)
	v_pk_add_f32 v[82:83], v[82:83], v[84:85]
	ds_bpermute_b32 v84, v182, v82
	ds_bpermute_b32 v85, v182, v83
	s_waitcnt lgkmcnt(0)
	v_pk_add_f32 v[82:83], v[82:83], v[84:85]
	s_nop 0
	v_pk_mul_f32 v[82:83], v[82:83], s[34:35] op_sel_hi:[1,0]
	s_nop 0
	v_fma_f32 v65, -v82, v82, v83
	v_max_f32_e32 v65, 0, v65
	v_add_f32_e32 v65, 0x3727c5ac, v65
	v_rsq_f32_e32 v84, v65
	v_pk_fma_f32 v[78:79], v[62:63], v[82:83], v[78:79] op_sel_hi:[1,0,1] neg_lo:[1,0,0] neg_hi:[1,0,0]
	v_pk_fma_f32 v[66:67], v[38:39], v[82:83], v[66:67] op_sel_hi:[1,0,1] neg_lo:[1,0,0] neg_hi:[1,0,0]
	v_pk_fma_f32 v[68:69], v[40:41], v[82:83], v[68:69] op_sel_hi:[1,0,1]
	v_pk_fma_f32 v[78:79], v[78:79], v[84:85], v[58:59] op_sel_hi:[1,0,1]
	v_pk_fma_f32 v[80:81], v[158:159], v[82:83], v[80:81] op_sel_hi:[1,0,1]
	v_mul_f32_e32 v65, 0xbfb8aa3b, v78
	v_exp_f32_e32 v65, v65
	v_pk_fma_f32 v[74:75], v[46:47], v[82:83], v[74:75] op_sel_hi:[1,0,1] neg_lo:[1,0,0] neg_hi:[1,0,0]
	v_pk_fma_f32 v[76:77], v[48:49], v[82:83], v[76:77] op_sel_hi:[1,0,1]
	v_pk_fma_f32 v[70:71], v[54:55], v[82:83], v[70:71] op_sel_hi:[1,0,1] neg_lo:[1,0,0] neg_hi:[1,0,0]
	v_add_f32_e32 v65, 1.0, v65
	v_pk_fma_f32 v[72:73], v[56:57], v[82:83], v[72:73] op_sel_hi:[1,0,1]
	v_pk_fma_f32 v[82:83], v[68:69], v[84:85], v[36:37] op_sel_hi:[1,0,1]
	v_pk_fma_f32 v[68:69], v[66:67], v[84:85], v[34:35] op_sel_hi:[1,0,1]
	v_rcp_f32_e32 v66, v65
	v_mul_f32_e32 v65, 0xbfb8aa3b, v79
	v_exp_f32_e32 v65, v65
	v_pk_fma_f32 v[80:81], v[80:81], v[84:85], v[60:61] op_sel_hi:[1,0,1]
	v_pk_fma_f32 v[70:71], v[70:71], v[84:85], v[50:51] op_sel_hi:[1,0,1]
; DI float bperm(float v, int srclane) { return __int_as_float(__builtin_amdgcn_ds_bpermute(srclane << 2, __float_as_int(v))); }
; DI unsigned pk2(float lo, float hi) { const f32x2 v = {lo, hi}; const hwbf16x2 b = __builtin_convertvector(v, hwbf16x2); return __builtin_bit_cast(unsigned, b); }
; DI float silu_f(float x) { return x * __builtin_amdgcn_rcpf(1.0f + __expf(-x)); }
; DI void row_stats(const float* STAT, int row, int fq, int lane, float& mu, float& rstd) {
;     const f32x4 a = *(const f32x4*)(STAT + (size_t)row * 32 + fq * 8), b = *(const f32x4*)(STAT + (size_t)row * 32 + fq * 8 + 4);
;     float s = (a[0] + a[2]) + (b[0] + b[2]), q = (a[1] + a[3]) + (b[1] + b[3]);
;     s += bperm(s, lane ^ 16); q += bperm(q, lane ^ 16); s += bperm(s, lane ^ 32); q += bperm(q, lane ^ 32);
;     mu = s * (1.0f / 1024.0f); rstd = __builtin_amdgcn_rsqf(fmaxf(q * (1.0f / 1024.0f) - mu * mu, 0.f) + EPS);
; }
;     DI void operator()(const f32x4 (&acc)[2][2][4][2], const pg8::Unit& u, int wr, int wc, int fr, int fq) const {
;     ...
;             for (int m = 0; m < 4; ++m) { const int row = row0 + ai * 128 + m * 16; float mu, rstd; row_stats(STAT, row, fq, lane, mu, rstd);
;                 const f32x4 g0 = (acc[ai][0][m][0] - c1[0][0] * mu) * rstd + c2[0][0], g1 = (acc[ai][0][m][1] - c1[0][1] * mu) * rstd + c2[0][1];
;                 const f32x4 u0 = (acc[ai][1][m][0] - c1[1][0] * mu) * rstd + c2[1][0], u1 = (acc[ai][1][m][1] - c1[1][1] * mu) * rstd + c2[1][1];
;                 u32x4 w; w.x = pk2(silu_f(g0[0]) * u0[0], silu_f(g0[1]) * u0[1]); w.y = pk2(silu_f(g0[2]) * u0[2], silu_f(g0[3]) * u0[3]);
;                 w.z = pk2(silu_f(g1[0]) * u1[0], silu_f(g1[1]) * u1[1]); w.w = pk2(silu_f(g1[2]) * u1[2], silu_f(g1[3]) * u1[3]);
;                 *(u32x4*)(HID + (size_t)row * DFF + col0) = w; }
	v_pk_fma_f32 v[74:75], v[74:75], v[84:85], v[42:43] op_sel_hi:[1,0,1]
	v_add_f32_e32 v65, 1.0, v65
	v_rcp_f32_e32 v67, v65
	v_mul_f32_e32 v65, 0xbfb8aa3b, v80
	v_exp_f32_e32 v65, v65
	v_pk_fma_f32 v[72:73], v[72:73], v[84:85], v[52:53] op_sel_hi:[1,0,1]
	v_pk_mul_f32 v[66:67], v[78:79], v[66:67]
	v_pk_fma_f32 v[76:77], v[76:77], v[84:85], v[44:45] op_sel_hi:[1,0,1]
	v_add_f32_e32 v65, 1.0, v65
	v_pk_mul_f32 v[66:67], v[70:71], v[66:67]
	v_rcp_f32_e32 v70, v65
	v_mul_f32_e32 v65, 0xbfb8aa3b, v81
	v_exp_f32_e32 v65, v65
	v_cvt_pk_bf16_f32 v66, v66, v67
	v_add_f32_e32 v65, 1.0, v65
	v_rcp_f32_e32 v71, v65
	v_mul_f32_e32 v65, 0xbfb8aa3b, v74
	v_exp_f32_e32 v65, v65
	v_pk_mul_f32 v[70:71], v[80:81], v[70:71]
	s_nop 0
	v_pk_mul_f32 v[70:71], v[72:73], v[70:71]
	v_add_f32_e32 v65, 1.0, v65
	v_cvt_pk_bf16_f32 v67, v70, v71
	v_rcp_f32_e32 v70, v65
	v_mul_f32_e32 v65, 0xbfb8aa3b, v75
	v_exp_f32_e32 v65, v65
	s_nop 0
	v_add_f32_e32 v65, 1.0, v65
	v_rcp_f32_e32 v71, v65
	v_mul_f32_e32 v65, 0xbfb8aa3b, v76
	v_exp_f32_e32 v65, v65
	v_pk_mul_f32 v[70:71], v[74:75], v[70:71]
	s_nop 0
	v_pk_mul_f32 v[68:69], v[68:69], v[70:71]
	v_add_f32_e32 v65, 1.0, v65
	v_rcp_f32_e32 v70, v65
	v_mul_f32_e32 v65, 0xbfb8aa3b, v77
	v_exp_f32_e32 v65, v65
	v_cvt_pk_bf16_f32 v68, v68, v69
	v_add_f32_e32 v65, 1.0, v65
	v_rcp_f32_e32 v71, v65
	v_mad_i64_i32 v[64:65], s[2:3], v64, s15, v[150:151]
	v_lshl_add_u64 v[64:65], v[64:65], 0, v[152:153]
	v_pk_mul_f32 v[70:71], v[76:77], v[70:71]
	s_nop 0
	v_pk_mul_f32 v[70:71], v[82:83], v[70:71]
	s_nop 0
	v_cvt_pk_bf16_f32 v69, v70, v71
	global_store_dwordx4 v[64:65], v[66:69], off
	s_nop 1
	v_add_u32_e32 v68, 0xa0, v172
	v_ashrrev_i32_e32 v69, 31, v68
	v_lshlrev_b64 v[64:65], 7, v[68:69]
	v_lshl_add_u64 v[64:65], s[22:23], 0, v[64:65]
	v_lshl_add_u64 v[70:71], v[64:65], 0, v[174:175]
	global_load_dwordx4 v[64:67], v[70:71], off offset:16
	s_nop 0
	global_load_dwordx4 v[70:73], v[70:71], off
	s_waitcnt vmcnt(1)
	v_pk_add_f32 v[64:65], v[64:65], v[66:67]
	s_waitcnt vmcnt(0)
	v_pk_add_f32 v[70:71], v[70:71], v[72:73]
	s_nop 0
	v_pk_add_f32 v[64:65], v[70:71], v[64:65]
	ds_bpermute_b32 v66, v183, v64
	ds_bpermute_b32 v67, v183, v65
	s_waitcnt lgkmcnt(0)
	v_pk_add_f32 v[64:65], v[64:65], v[66:67]
	ds_bpermute_b32 v66, v182, v64
	ds_bpermute_b32 v67, v182, v65
	s_waitcnt lgkmcnt(0)
	v_pk_add_f32 v[64:65], v[64:65], v[66:67]
	s_nop 0
	v_pk_mul_f32 v[64:65], v[64:65], s[34:35] op_sel_hi:[1,0]
	s_nop 0
	v_fma_f32 v66, -v64, v64, v65
	v_max_f32_e32 v66, 0, v66
	v_add_f32_e32 v66, 0x3727c5ac, v66
	v_rsq_f32_e32 v66, v66
	v_pk_fma_f32 v[30:31], v[62:63], v[64:65], v[30:31] op_sel_hi:[1,0,1] neg_lo:[1,0,0] neg_hi:[1,0,0]
	v_pk_fma_f32 v[18:19], v[38:39], v[64:65], v[18:19] op_sel_hi:[1,0,1] neg_lo:[1,0,0] neg_hi:[1,0,0]
	v_pk_fma_f32 v[20:21], v[40:41], v[64:65], v[20:21] op_sel_hi:[1,0,1]
	v_pk_fma_f32 v[30:31], v[30:31], v[66:67], v[58:59] op_sel_hi:[1,0,1]
	v_pk_fma_f32 v[32:33], v[158:159], v[64:65], v[32:33] op_sel_hi:[1,0,1]
	v_pk_fma_f32 v[26:27], v[46:47], v[64:65], v[26:27] op_sel_hi:[1,0,1] neg_lo:[1,0,0] neg_hi:[1,0,0]
	v_pk_fma_f32 v[28:29], v[48:49], v[64:65], v[28:29] op_sel_hi:[1,0,1]
	v_pk_fma_f32 v[22:23], v[54:55], v[64:65], v[22:23] op_sel_hi:[1,0,1] neg_lo:[1,0,0] neg_hi:[1,0,0]
	v_pk_fma_f32 v[24:25], v[56:57], v[64:65], v[24:25] op_sel_hi:[1,0,1]
	v_pk_fma_f32 v[64:65], v[20:21], v[66:67], v[36:37] op_sel_hi:[1,0,1]
	v_pk_fma_f32 v[20:21], v[18:19], v[66:67], v[34:35] op_sel_hi:[1,0,1]
	v_mul_f32_e32 v18, 0xbfb8aa3b, v30
	v_mul_f32_e32 v19, 0xbfb8aa3b, v31
	v_exp_f32_e32 v18, v18
	v_exp_f32_e32 v19, v19
	v_pk_fma_f32 v[22:23], v[22:23], v[66:67], v[50:51] op_sel_hi:[1,0,1]
	v_pk_fma_f32 v[32:33], v[32:33], v[66:67], v[60:61] op_sel_hi:[1,0,1]
	v_add_f32_e32 v18, 1.0, v18
	v_add_f32_e32 v19, 1.0, v19
	v_rcp_f32_e32 v18, v18
	v_rcp_f32_e32 v19, v19
	v_pk_fma_f32 v[24:25], v[24:25], v[66:67], v[52:53] op_sel_hi:[1,0,1]
	v_pk_fma_f32 v[26:27], v[26:27], v[66:67], v[42:43] op_sel_hi:[1,0,1]
	v_pk_fma_f32 v[28:29], v[28:29], v[66:67], v[44:45] op_sel_hi:[1,0,1]
	v_pk_mul_f32 v[18:19], v[30:31], v[18:19]
	s_nop 0
	v_pk_mul_f32 v[18:19], v[22:23], v[18:19]
	s_nop 0
	v_cvt_pk_bf16_f32 v18, v18, v19
	v_mul_f32_e32 v19, 0xbfb8aa3b, v32
	v_exp_f32_e32 v19, v19
	s_nop 0
	v_add_f32_e32 v19, 1.0, v19
	v_rcp_f32_e32 v22, v19
	v_mul_f32_e32 v19, 0xbfb8aa3b, v33
	v_exp_f32_e32 v19, v19
	s_nop 0
	v_add_f32_e32 v19, 1.0, v19
	v_rcp_f32_e32 v23, v19
	s_nop 0
	v_pk_mul_f32 v[22:23], v[32:33], v[22:23]
	s_nop 0
	v_pk_mul_f32 v[22:23], v[24:25], v[22:23]
	s_nop 0
	v_cvt_pk_bf16_f32 v19, v22, v23
	v_mul_f32_e32 v22, 0xbfb8aa3b, v26
	v_mul_f32_e32 v23, 0xbfb8aa3b, v27
	v_exp_f32_e32 v22, v22
	v_exp_f32_e32 v23, v23
	v_add_f32_e32 v22, 1.0, v22
	v_add_f32_e32 v23, 1.0, v23
	v_rcp_f32_e32 v22, v22
	v_rcp_f32_e32 v23, v23
	s_nop 0
	v_pk_mul_f32 v[22:23], v[26:27], v[22:23]
	s_nop 0
	v_pk_mul_f32 v[20:21], v[20:21], v[22:23]
	s_nop 0
	v_cvt_pk_bf16_f32 v20, v20, v21
	v_mul_f32_e32 v21, 0xbfb8aa3b, v28
	v_exp_f32_e32 v21, v21
	s_nop 0
	v_add_f32_e32 v21, 1.0, v21
	v_rcp_f32_e32 v22, v21
	v_mul_f32_e32 v21, 0xbfb8aa3b, v29
	v_exp_f32_e32 v21, v21
	s_nop 0
	v_add_f32_e32 v21, 1.0, v21
	v_rcp_f32_e32 v23, v21
	s_nop 0
	v_pk_mul_f32 v[22:23], v[28:29], v[22:23]
	s_nop 0
	v_pk_mul_f32 v[22:23], v[64:65], v[22:23]
	s_nop 0
	v_cvt_pk_bf16_f32 v21, v22, v23
	v_mad_i64_i32 v[22:23], s[2:3], v68, s15, v[150:151]
	v_lshl_add_u64 v[22:23], v[22:23], 0, v[152:153]
	global_store_dwordx4 v[22:23], v[18:21], off
	v_add_u32_e32 v22, 0xb0, v172
	v_ashrrev_i32_e32 v23, 31, v22
	v_lshlrev_b64 v[18:19], 7, v[22:23]
	v_lshl_add_u64 v[18:19], s[22:23], 0, v[18:19]
	v_lshl_add_u64 v[24:25], v[18:19], 0, v[174:175]
	global_load_dwordx4 v[18:21], v[24:25], off offset:16
	s_nop 0
	global_load_dwordx4 v[24:27], v[24:25], off
	s_waitcnt vmcnt(1)
; #define PG8_BAR __builtin_amdgcn_s_barrier()
; DI unsigned pk2(float lo, float hi) { const f32x2 v = {lo, hi}; const hwbf16x2 b = __builtin_convertvector(v, hwbf16x2); return __builtin_bit_cast(unsigned, b); }
; DI float silu_f(float x) { return x * __builtin_amdgcn_rcpf(1.0f + __expf(-x)); }
; template <class Epi, class Sched, bool ALIGN_EPI = false, bool SP2 = false>
; __device__ __forceinline__ void gemm_phase(PG8_LAS unsigned char* lds, const Gemm g, const Sched& S, const Epi& E, int wv) {
;     ...
;         if constexpr (!Epi::AFTER_DRAIN) { E(acc, cur, wr, wc, fr, fq); S.done(cur); }
;         if (!has_next) break;
; #pragma unroll
;         for (int a = 0; a < 2; ++a)
; #pragma unroll
;             for (int b = 0; b < 2; ++b)
; #pragma unroll
;                 for (int m = 0; m < 4; ++m)
; #pragma unroll
;                     for (int n = 0; n < 2; ++n) acc[a][b][m][n] = (f32x4){0.f, 0.f, 0.f, 0.f};
;         cur = nxt; cA = nA; cB = nB; ++ui;
;         if constexpr (ALIGN_EPI) { if (wr == 1) PG8_BAR; }
;     DI void operator()(const f32x4 (&acc)[2][2][4][2], const pg8::Unit& u, int wr, int wc, int fr, int fq) const {
;     ...
;             for (int m = 0; m < 4; ++m) { const int row = row0 + ai * 128 + m * 16; float mu, rstd; row_stats(STAT, row, fq, lane, mu, rstd);
;                 const f32x4 g0 = (acc[ai][0][m][0] - c1[0][0] * mu) * rstd + c2[0][0], g1 = (acc[ai][0][m][1] - c1[0][1] * mu) * rstd + c2[0][1];
;                 const f32x4 u0 = (acc[ai][1][m][0] - c1[1][0] * mu) * rstd + c2[1][0], u1 = (acc[ai][1][m][1] - c1[1][1] * mu) * rstd + c2[1][1];
;                 u32x4 w; w.x = pk2(silu_f(g0[0]) * u0[0], silu_f(g0[1]) * u0[1]); w.y = pk2(silu_f(g0[2]) * u0[2], silu_f(g0[3]) * u0[3]);
;                 w.z = pk2(silu_f(g1[0]) * u1[0], silu_f(g1[1]) * u1[1]); w.w = pk2(silu_f(g1[2]) * u1[2], silu_f(g1[3]) * u1[3]);
;                 *(u32x4*)(HID + (size_t)row * DFF + col0) = w; }
	v_pk_add_f32 v[18:19], v[18:19], v[20:21]
	s_waitcnt vmcnt(0)
	v_pk_add_f32 v[24:25], v[24:25], v[26:27]
	s_nop 0
	v_pk_add_f32 v[18:19], v[24:25], v[18:19]
	ds_bpermute_b32 v20, v183, v18
	ds_bpermute_b32 v21, v183, v19
	s_waitcnt lgkmcnt(0)
	v_pk_add_f32 v[18:19], v[18:19], v[20:21]
	ds_bpermute_b32 v20, v182, v18
	ds_bpermute_b32 v21, v182, v19
	s_waitcnt lgkmcnt(0)
	v_pk_add_f32 v[18:19], v[18:19], v[20:21]
	s_nop 0
	v_pk_mul_f32 v[18:19], v[18:19], s[34:35] op_sel_hi:[1,0]
	s_nop 0
	v_fma_f32 v20, -v18, v18, v19
	v_max_f32_e32 v20, 0, v20
	v_add_f32_e32 v20, 0x3727c5ac, v20
	v_rsq_f32_e32 v20, v20
	v_pk_fma_f32 v[14:15], v[62:63], v[18:19], v[14:15] op_sel_hi:[1,0,1] neg_lo:[1,0,0] neg_hi:[1,0,0]
	v_pk_fma_f32 v[2:3], v[38:39], v[18:19], v[2:3] op_sel_hi:[1,0,1] neg_lo:[1,0,0] neg_hi:[1,0,0]
	v_pk_fma_f32 v[4:5], v[40:41], v[18:19], v[4:5] op_sel_hi:[1,0,1]
	v_pk_fma_f32 v[14:15], v[14:15], v[20:21], v[58:59] op_sel_hi:[1,0,1]
	v_pk_fma_f32 v[16:17], v[158:159], v[18:19], v[16:17] op_sel_hi:[1,0,1]
	v_pk_fma_f32 v[10:11], v[46:47], v[18:19], v[10:11] op_sel_hi:[1,0,1] neg_lo:[1,0,0] neg_hi:[1,0,0]
	v_pk_fma_f32 v[12:13], v[48:49], v[18:19], v[12:13] op_sel_hi:[1,0,1]
	v_pk_fma_f32 v[6:7], v[54:55], v[18:19], v[6:7] op_sel_hi:[1,0,1] neg_lo:[1,0,0] neg_hi:[1,0,0]
	v_pk_fma_f32 v[8:9], v[56:57], v[18:19], v[8:9] op_sel_hi:[1,0,1]
	v_pk_fma_f32 v[18:19], v[4:5], v[20:21], v[36:37] op_sel_hi:[1,0,1]
	v_pk_fma_f32 v[4:5], v[2:3], v[20:21], v[34:35] op_sel_hi:[1,0,1]
	v_mul_f32_e32 v2, 0xbfb8aa3b, v14
	v_mul_f32_e32 v3, 0xbfb8aa3b, v15
	v_exp_f32_e32 v2, v2
	v_exp_f32_e32 v3, v3
	v_pk_fma_f32 v[6:7], v[6:7], v[20:21], v[50:51] op_sel_hi:[1,0,1]
	v_pk_fma_f32 v[16:17], v[16:17], v[20:21], v[60:61] op_sel_hi:[1,0,1]
	v_add_f32_e32 v2, 1.0, v2
	v_add_f32_e32 v3, 1.0, v3
	v_rcp_f32_e32 v2, v2
	v_rcp_f32_e32 v3, v3
	v_pk_fma_f32 v[8:9], v[8:9], v[20:21], v[52:53] op_sel_hi:[1,0,1]
	v_pk_fma_f32 v[10:11], v[10:11], v[20:21], v[42:43] op_sel_hi:[1,0,1]
	v_pk_fma_f32 v[12:13], v[12:13], v[20:21], v[44:45] op_sel_hi:[1,0,1]
	v_pk_mul_f32 v[2:3], v[14:15], v[2:3]
	s_nop 0
	v_pk_mul_f32 v[2:3], v[6:7], v[2:3]
	s_nop 0
	v_cvt_pk_bf16_f32 v2, v2, v3
	v_mul_f32_e32 v3, 0xbfb8aa3b, v16
	v_exp_f32_e32 v3, v3
	s_nop 0
	v_add_f32_e32 v3, 1.0, v3
	v_rcp_f32_e32 v6, v3
	v_mul_f32_e32 v3, 0xbfb8aa3b, v17
	v_exp_f32_e32 v3, v3
	s_nop 0
	v_add_f32_e32 v3, 1.0, v3
	v_rcp_f32_e32 v7, v3
	s_nop 0
	v_pk_mul_f32 v[6:7], v[16:17], v[6:7]
	s_nop 0
	v_pk_mul_f32 v[6:7], v[8:9], v[6:7]
	s_nop 0
	v_cvt_pk_bf16_f32 v3, v6, v7
	v_mul_f32_e32 v6, 0xbfb8aa3b, v10
	v_mul_f32_e32 v7, 0xbfb8aa3b, v11
	v_exp_f32_e32 v6, v6
	v_exp_f32_e32 v7, v7
	v_add_f32_e32 v6, 1.0, v6
	v_add_f32_e32 v7, 1.0, v7
	v_rcp_f32_e32 v6, v6
	v_rcp_f32_e32 v7, v7
	s_nop 0
	v_pk_mul_f32 v[6:7], v[10:11], v[6:7]
	s_nop 0
	v_pk_mul_f32 v[4:5], v[4:5], v[6:7]
	s_nop 0
	v_cvt_pk_bf16_f32 v4, v4, v5
	v_mul_f32_e32 v5, 0xbfb8aa3b, v12
	v_exp_f32_e32 v5, v5
	s_nop 0
	v_add_f32_e32 v5, 1.0, v5
	v_rcp_f32_e32 v6, v5
	v_mul_f32_e32 v5, 0xbfb8aa3b, v13
	v_exp_f32_e32 v5, v5
	s_nop 0
	v_add_f32_e32 v5, 1.0, v5
	v_rcp_f32_e32 v7, v5
	s_nop 0
	v_pk_mul_f32 v[6:7], v[12:13], v[6:7]
	s_nop 0
	v_pk_mul_f32 v[6:7], v[18:19], v[6:7]
	s_nop 0
	v_cvt_pk_bf16_f32 v5, v6, v7
	v_mad_i64_i32 v[6:7], s[2:3], v22, s15, v[150:151]
	v_lshl_add_u64 v[6:7], v[6:7], 0, v[152:153]
	s_mov_b64 s[2:3], -1
	global_store_dwordx4 v[6:7], v[2:5], off
	s_cbranch_vccnz .LBB0_1889
	s_andn2_b64 vcc, exec, s[18:19]
	s_cbranch_vccnz .LBB0_1888
	s_barrier
	s_branch .LBB0_1888
